# big-GEMM K-loops: additionally s_setprio 1 moved in front of the pre-MFMA barrier so the first MFMA issues right after the release
# baseline (speedup 1.0000x reference)
; #define PG8_STAGE(bufoff, gbase, voff) do { _Pragma("unroll") for (int _i = 0; _i < 2; ++_i) \
;         __builtin_amdgcn_global_load_lds((const unsigned*)((const char*)(gbase) + (voff)[_i]), (PG8_LAS unsigned*)(lds + (bufoff) + ldsw + _i * 8192), 16, 0, 0); } while (0)
; #define PG8_LDA(dst, b, h) do { _Pragma("unroll") for (int m = 0; m < 4; ++m) _Pragma("unroll") for (int k = 0; k < 2; ++k) dst[m][k] = *(const PG8_LAS bf16x8*)(lds + PG8_SA(b, h) + aoff + m * 2048 + k * 1024); } while (0)
; #define PG8_LDB(dst, b, h) do { _Pragma("unroll") for (int n = 0; n < 2; ++n) _Pragma("unroll") for (int k = 0; k < 2; ++k) dst[n][k] = *(const PG8_LAS bf16x8*)(lds + PG8_SB(b, h) + boff + n * 2048 + k * 1024); } while (0)
; #define PG8_MMA(ai, bj, At, Bt) do { __builtin_amdgcn_s_setprio(1); _Pragma("unroll") for (int m = 0; m < 4; ++m) _Pragma("unroll") for (int n = 0; n < 2; ++n) _Pragma("unroll") for (int k = 0; k < 2; ++k) \
;         acc[ai][bj][m][n] = __builtin_amdgcn_mfma_f32_16x16x32_bf16(Bt[n][k], At[m][k], acc[ai][bj][m][n], 0, 0, 0); __builtin_amdgcn_s_setprio(0); } while (0)
; #define PG8_WAIT_V(n) asm volatile("s_waitcnt vmcnt(" #n ")" ::: "memory")
; #define PG8_WAIT_L(n) asm volatile("s_waitcnt lgkmcnt(" #n ")" ::: "memory")
; #define PG8_BAR __builtin_amdgcn_s_barrier()
; #define PG8_SCHED __builtin_amdgcn_sched_barrier(0)
; template <class Epi, class Sched, bool ALIGN_EPI = false, bool SP2 = false>
; __device__ __forceinline__ void gemm_phase(PG8_LAS unsigned char* lds, const Gemm g, const Sched& S, const Epi& E) {
;     ...
;             const char* a2 = last ? nA : cA + (size_t)(t + 2) * kstep; const char* b2 = last ? nB : cB + (size_t)(t + 2) * kstep;
;             const char* a3 = a2 + kstep; const char* b3 = b2 + kstep;
;             if (last && has_next) S.a_ready(nxt);
;             if constexpr (SP2) {
;             PG8_LDB(B0, 0, 0); PG8_LDB(B1, 0, 1); PG8_SCHED; PG8_LDA(At, 0, 0); PG8_STAGE(PG8_SA(1, 1), a1 + hstep, voffA);
;             PG8_WAIT_V(8); PG8_WAIT_L(0); PG8_BAR; PG8_MMA(0, 0, At, B0); PG8_MMA(0, 1, At, B1); PG8_BAR; PG8_SCHED;
;             PG8_LDA(At, 0, 1); PG8_STAGE(PG8_SB(0, 0), b2, voffB); PG8_STAGE(PG8_SB(0, 1), b2 + hstep, voffB); PG8_STAGE(PG8_SA(0, 0), a2, voffA);
;             PG8_WAIT_V(8); PG8_WAIT_L(0); PG8_BAR; PG8_MMA(1, 0, At, B0); PG8_MMA(1, 1, At, B1); PG8_BAR; PG8_SCHED;
.LBB0_253:
	ds_read_b128 v[148:151], v161
	ds_read_b128 v[166:169], v161 offset:1024
	ds_read_b128 v[170:173], v161 offset:2048
	ds_read_b128 v[174:177], v161 offset:3072
	ds_read_b128 v[178:181], v162
	ds_read_b128 v[184:187], v162 offset:1024
	ds_read_b128 v[188:191], v162 offset:2048
	ds_read_b128 v[192:195], v162 offset:3072
	s_add_u32 s30, s28, 0xfff80080
	s_addc_u32 s31, s29, -1
	s_cmp_eq_u32 s56, 28
	s_cselect_b32 s35, s3, s31
	s_cselect_b32 s34, s21, s30
	s_cselect_b32 s31, s19, s55
	s_cselect_b32 s30, s27, s54
	v_lshl_add_u64 v[152:153], s[28:29], 0, v[140:141]
	s_add_i32 m0, s38, 0xc000
	ds_read_b128 v[196:199], v163
	ds_read_b128 v[200:203], v163 offset:1024
	ds_read_b128 v[204:207], v163 offset:2048
	ds_read_b128 v[208:211], v163 offset:3072
	ds_read_b128 v[212:215], v163 offset:4096
	ds_read_b128 v[216:219], v163 offset:5120
	ds_read_b128 v[220:223], v163 offset:6144
	ds_read_b128 v[224:227], v163 offset:7168
	global_load_lds_dwordx4 v[152:153], off
	v_lshl_add_u64 v[152:153], s[28:29], 0, v[142:143]
	s_add_i32 m0, s38, 0xe000
	s_nop 0
	global_load_lds_dwordx4 v[152:153], off
	s_waitcnt vmcnt(8)
	s_waitcnt lgkmcnt(0)
	s_setprio 1
	s_barrier
	s_waitcnt lgkmcnt(0)
	v_mfma_f32_16x16x32_bf16 v[124:127], v[148:151], v[196:199], v[124:127]
	v_mfma_f32_16x16x32_bf16 v[120:123], v[170:173], v[196:199], v[120:123]
	v_mfma_f32_16x16x32_bf16 v[116:119], v[148:151], v[204:207], v[116:119]
	v_mfma_f32_16x16x32_bf16 v[112:115], v[170:173], v[204:207], v[112:115]
	v_mfma_f32_16x16x32_bf16 v[108:111], v[148:151], v[212:215], v[108:111]
	v_mfma_f32_16x16x32_bf16 v[104:107], v[170:173], v[212:215], v[104:107]
	v_mfma_f32_16x16x32_bf16 v[100:103], v[148:151], v[220:223], v[100:103]
	v_mfma_f32_16x16x32_bf16 v[96:99], v[170:173], v[220:223], v[96:99]
	v_mfma_f32_16x16x32_bf16 v[124:127], v[166:169], v[200:203], v[124:127]
	v_mfma_f32_16x16x32_bf16 v[120:123], v[174:177], v[200:203], v[120:123]
	v_mfma_f32_16x16x32_bf16 v[116:119], v[166:169], v[208:211], v[116:119]
	v_mfma_f32_16x16x32_bf16 v[112:115], v[174:177], v[208:211], v[112:115]
	v_mfma_f32_16x16x32_bf16 v[108:111], v[166:169], v[216:219], v[108:111]
	v_mfma_f32_16x16x32_bf16 v[104:107], v[174:177], v[216:219], v[104:107]
	v_mfma_f32_16x16x32_bf16 v[100:103], v[166:169], v[224:227], v[100:103]
	v_mfma_f32_16x16x32_bf16 v[96:99], v[174:177], v[224:227], v[96:99]
	s_setprio 0
	s_setprio 1
	v_mfma_f32_16x16x32_bf16 v[92:95], v[178:181], v[196:199], v[92:95]
	v_mfma_f32_16x16x32_bf16 v[88:91], v[188:191], v[196:199], v[88:91]
	v_mfma_f32_16x16x32_bf16 v[84:87], v[178:181], v[204:207], v[84:87]
	v_mfma_f32_16x16x32_bf16 v[80:83], v[188:191], v[204:207], v[80:83]
	v_mfma_f32_16x16x32_bf16 v[76:79], v[178:181], v[212:215], v[76:79]
	v_mfma_f32_16x16x32_bf16 v[72:75], v[188:191], v[212:215], v[72:75]
	v_mfma_f32_16x16x32_bf16 v[68:71], v[178:181], v[220:223], v[68:71]
	v_mfma_f32_16x16x32_bf16 v[64:67], v[188:191], v[220:223], v[64:67]
	v_mfma_f32_16x16x32_bf16 v[92:95], v[184:187], v[200:203], v[92:95]
	v_mfma_f32_16x16x32_bf16 v[88:91], v[192:195], v[200:203], v[88:91]
	v_mfma_f32_16x16x32_bf16 v[84:87], v[184:187], v[208:211], v[84:87]
	v_mfma_f32_16x16x32_bf16 v[80:83], v[192:195], v[208:211], v[80:83]
	v_mfma_f32_16x16x32_bf16 v[76:79], v[184:187], v[216:219], v[76:79]
	v_mfma_f32_16x16x32_bf16 v[72:75], v[192:195], v[216:219], v[72:75]
	v_mfma_f32_16x16x32_bf16 v[68:71], v[184:187], v[224:227], v[68:71]
	v_mfma_f32_16x16x32_bf16 v[64:67], v[192:195], v[224:227], v[64:67]
	s_barrier
	s_setprio 0
	s_add_i32 s57, s48, s37
	v_lshl_add_u64 v[152:153], s[30:31], 0, v[130:131]
	s_mov_b32 m0, s57
	ds_read_b128 v[196:199], v163 offset:16384
	ds_read_b128 v[200:203], v163 offset:17408
	ds_read_b128 v[204:207], v163 offset:18432
	ds_read_b128 v[208:211], v163 offset:19456
	ds_read_b128 v[212:215], v163 offset:20480
	ds_read_b128 v[216:219], v163 offset:21504
	ds_read_b128 v[220:223], v163 offset:22528
	ds_read_b128 v[224:227], v163 offset:23552
	global_load_lds_dwordx4 v[152:153], off
	s_add_i32 m0, s57, 0x2000
	s_add_u32 s58, s30, 0x80000
	v_lshl_add_u64 v[228:229], s[30:31], 0, v[134:135]
	s_addc_u32 s59, s31, 0
	s_add_i32 s57, s49, s37
	global_load_lds_dwordx4 v[228:229], off
	v_lshl_add_u64 v[230:231], s[58:59], 0, v[130:131]
	s_mov_b32 m0, s57
	v_lshl_add_u64 v[232:233], s[34:35], 0, v[132:133]
	global_load_lds_dwordx4 v[230:231], off
	v_lshl_add_u64 v[230:231], s[58:59], 0, v[134:135]
	s_add_i32 m0, s57, 0x2000
	s_nop 0
	global_load_lds_dwordx4 v[230:231], off
	v_lshl_add_u64 v[230:231], s[34:35], 0, v[128:129]
	s_mov_b32 m0, s38
	s_nop 0
	global_load_lds_dwordx4 v[230:231], off
	s_mov_b32 m0, s39
	s_nop 0
	global_load_lds_dwordx4 v[232:233], off
	s_waitcnt vmcnt(8)
	s_waitcnt lgkmcnt(0)
	s_setprio 1
	s_barrier
; #define PG8_STAGE(bufoff, gbase, voff) do { _Pragma("unroll") for (int _i = 0; _i < 2; ++_i) \
;         __builtin_amdgcn_global_load_lds((const unsigned*)((const char*)(gbase) + (voff)[_i]), (PG8_LAS unsigned*)(lds + (bufoff) + ldsw + _i * 8192), 16, 0, 0); } while (0)
; #define PG8_LDA(dst, b, h) do { _Pragma("unroll") for (int m = 0; m < 4; ++m) _Pragma("unroll") for (int k = 0; k < 2; ++k) dst[m][k] = *(const PG8_LAS bf16x8*)(lds + PG8_SA(b, h) + aoff + m * 2048 + k * 1024); } while (0)
; #define PG8_LDB(dst, b, h) do { _Pragma("unroll") for (int n = 0; n < 2; ++n) _Pragma("unroll") for (int k = 0; k < 2; ++k) dst[n][k] = *(const PG8_LAS bf16x8*)(lds + PG8_SB(b, h) + boff + n * 2048 + k * 1024); } while (0)
; #define PG8_MMA(ai, bj, At, Bt) do { __builtin_amdgcn_s_setprio(1); _Pragma("unroll") for (int m = 0; m < 4; ++m) _Pragma("unroll") for (int n = 0; n < 2; ++n) _Pragma("unroll") for (int k = 0; k < 2; ++k) \
;         acc[ai][bj][m][n] = __builtin_amdgcn_mfma_f32_16x16x32_bf16(Bt[n][k], At[m][k], acc[ai][bj][m][n], 0, 0, 0); __builtin_amdgcn_s_setprio(0); } while (0)
; #define PG8_WAIT_V(n) asm volatile("s_waitcnt vmcnt(" #n ")" ::: "memory")
; #define PG8_WAIT_L(n) asm volatile("s_waitcnt lgkmcnt(" #n ")" ::: "memory")
; #define PG8_BAR __builtin_amdgcn_s_barrier()
; #define PG8_SCHED __builtin_amdgcn_sched_barrier(0)
; template <class Epi, class Sched, bool ALIGN_EPI = false, bool SP2 = false>
; __device__ __forceinline__ void gemm_phase(PG8_LAS unsigned char* lds, const Gemm g, const Sched& S, const Epi& E) {
;     ...
;             PG8_WAIT_V(8); PG8_WAIT_L(0); PG8_BAR; PG8_MMA(1, 0, At, B0); PG8_MMA(1, 1, At, B1); PG8_BAR; PG8_SCHED;
;             PG8_LDB(B0, 1, 0); PG8_LDB(B1, 1, 1); PG8_SCHED; PG8_LDA(At, 1, 0); PG8_STAGE(PG8_SA(0, 1), a2 + hstep, voffA);
;             PG8_WAIT_V(8); PG8_WAIT_L(0); PG8_BAR; PG8_MMA(0, 0, At, B0); PG8_MMA(0, 1, At, B1); PG8_BAR; PG8_SCHED;
	s_waitcnt lgkmcnt(0)
	v_mfma_f32_16x16x32_bf16 v[60:63], v[148:151], v[196:199], v[60:63]
	v_mfma_f32_16x16x32_bf16 v[56:59], v[170:173], v[196:199], v[56:59]
	v_mfma_f32_16x16x32_bf16 v[52:55], v[148:151], v[204:207], v[52:55]
	v_mfma_f32_16x16x32_bf16 v[48:51], v[170:173], v[204:207], v[48:51]
	v_mfma_f32_16x16x32_bf16 v[44:47], v[148:151], v[212:215], v[44:47]
	v_mfma_f32_16x16x32_bf16 v[40:43], v[170:173], v[212:215], v[40:43]
	v_mfma_f32_16x16x32_bf16 v[36:39], v[148:151], v[220:223], v[36:39]
	v_mfma_f32_16x16x32_bf16 v[32:35], v[170:173], v[220:223], v[32:35]
	v_mfma_f32_16x16x32_bf16 v[60:63], v[166:169], v[200:203], v[60:63]
	v_mfma_f32_16x16x32_bf16 v[56:59], v[174:177], v[200:203], v[56:59]
	v_mfma_f32_16x16x32_bf16 v[52:55], v[166:169], v[208:211], v[52:55]
	v_mfma_f32_16x16x32_bf16 v[48:51], v[174:177], v[208:211], v[48:51]
	v_mfma_f32_16x16x32_bf16 v[44:47], v[166:169], v[216:219], v[44:47]
	v_mfma_f32_16x16x32_bf16 v[40:43], v[174:177], v[216:219], v[40:43]
	v_mfma_f32_16x16x32_bf16 v[36:39], v[166:169], v[224:227], v[36:39]
	v_mfma_f32_16x16x32_bf16 v[32:35], v[174:177], v[224:227], v[32:35]
	s_setprio 0
	s_setprio 1
	v_mfma_f32_16x16x32_bf16 v[28:31], v[178:181], v[196:199], v[28:31]
	v_mfma_f32_16x16x32_bf16 v[24:27], v[188:191], v[196:199], v[24:27]
	v_mfma_f32_16x16x32_bf16 v[20:23], v[178:181], v[204:207], v[20:23]
	v_mfma_f32_16x16x32_bf16 v[16:19], v[188:191], v[204:207], v[16:19]
	v_mfma_f32_16x16x32_bf16 v[12:15], v[178:181], v[212:215], v[12:15]
	v_mfma_f32_16x16x32_bf16 v[8:11], v[188:191], v[212:215], v[8:11]
	v_mfma_f32_16x16x32_bf16 v[4:7], v[178:181], v[220:223], v[4:7]
	v_mfma_f32_16x16x32_bf16 v[0:3], v[188:191], v[220:223], v[0:3]
	v_mfma_f32_16x16x32_bf16 v[28:31], v[184:187], v[200:203], v[28:31]
	v_mfma_f32_16x16x32_bf16 v[24:27], v[192:195], v[200:203], v[24:27]
	v_mfma_f32_16x16x32_bf16 v[20:23], v[184:187], v[208:211], v[20:23]
	v_mfma_f32_16x16x32_bf16 v[16:19], v[192:195], v[208:211], v[16:19]
	v_mfma_f32_16x16x32_bf16 v[12:15], v[184:187], v[216:219], v[12:15]
	v_mfma_f32_16x16x32_bf16 v[8:11], v[192:195], v[216:219], v[8:11]
	v_mfma_f32_16x16x32_bf16 v[4:7], v[184:187], v[224:227], v[4:7]
	v_mfma_f32_16x16x32_bf16 v[0:3], v[192:195], v[224:227], v[0:3]
	s_barrier
	s_setprio 0
	s_add_i32 s57, 0, 0x18000
	v_add_u32_e32 v136, s57, v159
	s_add_i32 s58, 0, 0x1c000
	ds_read_b128 v[148:151], v136
	ds_read_b128 v[166:169], v136 offset:1024
	ds_read_b128 v[170:173], v136 offset:2048
	ds_read_b128 v[174:177], v136 offset:3072
	v_add_u32_e32 v136, s58, v159
	ds_read_b128 v[178:181], v136
	ds_read_b128 v[184:187], v136 offset:1024
	ds_read_b128 v[188:191], v136 offset:2048
	ds_read_b128 v[192:195], v136 offset:3072
	s_add_u32 s34, s34, 0x80000
	s_addc_u32 s35, s35, 0
	s_mov_b32 m0, s40
	v_lshl_add_u64 v[234:235], s[34:35], 0, v[128:129]
	ds_read_b128 v[196:199], v163 offset:32768
	ds_read_b128 v[200:203], v163 offset:33792
	ds_read_b128 v[204:207], v163 offset:34816
	ds_read_b128 v[208:211], v163 offset:35840
	ds_read_b128 v[212:215], v163 offset:36864
	ds_read_b128 v[216:219], v163 offset:37888
	ds_read_b128 v[220:223], v163 offset:38912
	ds_read_b128 v[224:227], v163 offset:39936
	global_load_lds_dwordx4 v[234:235], off
	v_lshl_add_u64 v[234:235], s[34:35], 0, v[132:133]
	s_mov_b32 m0, s41
	s_nop 0
	global_load_lds_dwordx4 v[234:235], off
	s_waitcnt vmcnt(8)
	s_waitcnt lgkmcnt(0)
	s_setprio 1
	s_barrier
	s_waitcnt lgkmcnt(0)
	v_mfma_f32_16x16x32_bf16 v[124:127], v[148:151], v[196:199], v[124:127]
	v_mfma_f32_16x16x32_bf16 v[120:123], v[170:173], v[196:199], v[120:123]
	v_mfma_f32_16x16x32_bf16 v[116:119], v[148:151], v[204:207], v[116:119]
	v_mfma_f32_16x16x32_bf16 v[112:115], v[170:173], v[204:207], v[112:115]
	v_mfma_f32_16x16x32_bf16 v[108:111], v[148:151], v[212:215], v[108:111]
	v_mfma_f32_16x16x32_bf16 v[104:107], v[170:173], v[212:215], v[104:107]
	v_mfma_f32_16x16x32_bf16 v[100:103], v[148:151], v[220:223], v[100:103]
	v_mfma_f32_16x16x32_bf16 v[96:99], v[170:173], v[220:223], v[96:99]
	v_mfma_f32_16x16x32_bf16 v[124:127], v[166:169], v[200:203], v[124:127]
	v_mfma_f32_16x16x32_bf16 v[120:123], v[174:177], v[200:203], v[120:123]
	v_mfma_f32_16x16x32_bf16 v[116:119], v[166:169], v[208:211], v[116:119]
	v_mfma_f32_16x16x32_bf16 v[112:115], v[174:177], v[208:211], v[112:115]
	v_mfma_f32_16x16x32_bf16 v[108:111], v[166:169], v[216:219], v[108:111]
	v_mfma_f32_16x16x32_bf16 v[104:107], v[174:177], v[216:219], v[104:107]
	v_mfma_f32_16x16x32_bf16 v[100:103], v[166:169], v[224:227], v[100:103]
	v_mfma_f32_16x16x32_bf16 v[96:99], v[174:177], v[224:227], v[96:99]
	s_setprio 0
	s_setprio 1
	v_mfma_f32_16x16x32_bf16 v[92:95], v[178:181], v[196:199], v[92:95]
	v_mfma_f32_16x16x32_bf16 v[88:91], v[188:191], v[196:199], v[88:91]
	v_mfma_f32_16x16x32_bf16 v[84:87], v[178:181], v[204:207], v[84:87]
	v_mfma_f32_16x16x32_bf16 v[80:83], v[188:191], v[204:207], v[80:83]
	v_mfma_f32_16x16x32_bf16 v[76:79], v[178:181], v[212:215], v[76:79]
	v_mfma_f32_16x16x32_bf16 v[72:75], v[188:191], v[212:215], v[72:75]
	v_mfma_f32_16x16x32_bf16 v[68:71], v[178:181], v[220:223], v[68:71]
	v_mfma_f32_16x16x32_bf16 v[64:67], v[188:191], v[220:223], v[64:67]
	v_mfma_f32_16x16x32_bf16 v[92:95], v[184:187], v[200:203], v[92:95]
	v_mfma_f32_16x16x32_bf16 v[88:91], v[192:195], v[200:203], v[88:91]
	v_mfma_f32_16x16x32_bf16 v[84:87], v[184:187], v[208:211], v[84:87]
	v_mfma_f32_16x16x32_bf16 v[80:83], v[192:195], v[208:211], v[80:83]
	v_mfma_f32_16x16x32_bf16 v[76:79], v[184:187], v[216:219], v[76:79]
	v_mfma_f32_16x16x32_bf16 v[72:75], v[192:195], v[216:219], v[72:75]
	v_mfma_f32_16x16x32_bf16 v[68:71], v[184:187], v[224:227], v[68:71]
	v_mfma_f32_16x16x32_bf16 v[64:67], v[192:195], v[224:227], v[64:67]
	s_barrier
; #define PG8_STAGE(bufoff, gbase, voff) do { _Pragma("unroll") for (int _i = 0; _i < 2; ++_i) \
;         __builtin_amdgcn_global_load_lds((const unsigned*)((const char*)(gbase) + (voff)[_i]), (PG8_LAS unsigned*)(lds + (bufoff) + ldsw + _i * 8192), 16, 0, 0); } while (0)
; #define PG8_LDA(dst, b, h) do { _Pragma("unroll") for (int m = 0; m < 4; ++m) _Pragma("unroll") for (int k = 0; k < 2; ++k) dst[m][k] = *(const PG8_LAS bf16x8*)(lds + PG8_SA(b, h) + aoff + m * 2048 + k * 1024); } while (0)
; #define PG8_MMA(ai, bj, At, Bt) do { __builtin_amdgcn_s_setprio(1); _Pragma("unroll") for (int m = 0; m < 4; ++m) _Pragma("unroll") for (int n = 0; n < 2; ++n) _Pragma("unroll") for (int k = 0; k < 2; ++k) \
;         acc[ai][bj][m][n] = __builtin_amdgcn_mfma_f32_16x16x32_bf16(Bt[n][k], At[m][k], acc[ai][bj][m][n], 0, 0, 0); __builtin_amdgcn_s_setprio(0); } while (0)
; #define PG8_WAIT_V(n) asm volatile("s_waitcnt vmcnt(" #n ")" ::: "memory")
; #define PG8_WAIT_L(n) asm volatile("s_waitcnt lgkmcnt(" #n ")" ::: "memory")
; #define PG8_BAR __builtin_amdgcn_s_barrier()
; #define PG8_SCHED __builtin_amdgcn_sched_barrier(0)
; template <class Epi, class Sched, bool ALIGN_EPI = false, bool SP2 = false>
; __device__ __forceinline__ void gemm_phase(PG8_LAS unsigned char* lds, const Gemm g, const Sched& S, const Epi& E) {
;     ...
;             PG8_LDA(At, 1, 1); PG8_STAGE(PG8_SB(1, 0), b3, voffB); PG8_STAGE(PG8_SB(1, 1), b3 + hstep, voffB); PG8_STAGE(PG8_SA(1, 0), a3, voffA);
;             PG8_WAIT_V(8); PG8_WAIT_L(0); PG8_BAR; PG8_MMA(1, 0, At, B0); PG8_MMA(1, 1, At, B1); PG8_BAR; PG8_SCHED;
	s_setprio 0
	s_add_i32 s34, s57, s37
	v_lshl_add_u64 v[152:153], v[152:153], 0, s[14:15]
	s_mov_b32 m0, s34
	ds_read_b128 v[196:199], v163 offset:49152
	ds_read_b128 v[200:203], v163 offset:50176
	ds_read_b128 v[204:207], v163 offset:51200
	ds_read_b128 v[208:211], v163 offset:52224
	ds_read_b128 v[212:215], v163 offset:53248
	ds_read_b128 v[216:219], v163 offset:54272
	ds_read_b128 v[220:223], v163 offset:55296
	ds_read_b128 v[224:227], v163 offset:56320
	global_load_lds_dwordx4 v[152:153], off
	s_add_i32 m0, s34, 0x2000
	s_add_u32 s30, s30, 0x80080
	v_lshl_add_u64 v[152:153], v[228:229], 0, s[14:15]
	s_addc_u32 s31, s31, 0
	s_add_i32 s34, s58, s37
	global_load_lds_dwordx4 v[152:153], off
	v_lshl_add_u64 v[152:153], s[30:31], 0, v[130:131]
	s_mov_b32 m0, s34
	s_nop 0
	global_load_lds_dwordx4 v[152:153], off
	v_lshl_add_u64 v[152:153], s[30:31], 0, v[134:135]
	s_add_i32 m0, s34, 0x2000
	s_nop 0
	global_load_lds_dwordx4 v[152:153], off
	v_lshl_add_u64 v[152:153], v[230:231], 0, s[14:15]
	s_mov_b32 m0, s43
	s_nop 0
	global_load_lds_dwordx4 v[152:153], off
	v_lshl_add_u64 v[152:153], v[232:233], 0, s[14:15]
	s_mov_b32 m0, s44
	s_nop 0
	global_load_lds_dwordx4 v[152:153], off
	s_waitcnt vmcnt(8)
	s_waitcnt lgkmcnt(0)
	s_setprio 1
	s_barrier
	s_waitcnt lgkmcnt(0)
	v_mfma_f32_16x16x32_bf16 v[60:63], v[148:151], v[196:199], v[60:63]
	v_mfma_f32_16x16x32_bf16 v[56:59], v[170:173], v[196:199], v[56:59]
	v_mfma_f32_16x16x32_bf16 v[52:55], v[148:151], v[204:207], v[52:55]
	v_mfma_f32_16x16x32_bf16 v[48:51], v[170:173], v[204:207], v[48:51]
	v_mfma_f32_16x16x32_bf16 v[44:47], v[148:151], v[212:215], v[44:47]
	v_mfma_f32_16x16x32_bf16 v[40:43], v[170:173], v[212:215], v[40:43]
	v_mfma_f32_16x16x32_bf16 v[36:39], v[148:151], v[220:223], v[36:39]
	v_mfma_f32_16x16x32_bf16 v[32:35], v[170:173], v[220:223], v[32:35]
	v_mfma_f32_16x16x32_bf16 v[60:63], v[166:169], v[200:203], v[60:63]
	v_mfma_f32_16x16x32_bf16 v[56:59], v[174:177], v[200:203], v[56:59]
	v_mfma_f32_16x16x32_bf16 v[52:55], v[166:169], v[208:211], v[52:55]
	v_mfma_f32_16x16x32_bf16 v[48:51], v[174:177], v[208:211], v[48:51]
	v_mfma_f32_16x16x32_bf16 v[44:47], v[166:169], v[216:219], v[44:47]
	v_mfma_f32_16x16x32_bf16 v[40:43], v[174:177], v[216:219], v[40:43]
	v_mfma_f32_16x16x32_bf16 v[36:39], v[166:169], v[224:227], v[36:39]
	v_mfma_f32_16x16x32_bf16 v[32:35], v[174:177], v[224:227], v[32:35]
	s_setprio 0
	s_setprio 1
	v_mfma_f32_16x16x32_bf16 v[28:31], v[178:181], v[196:199], v[28:31]
	v_mfma_f32_16x16x32_bf16 v[24:27], v[188:191], v[196:199], v[24:27]
	v_mfma_f32_16x16x32_bf16 v[20:23], v[178:181], v[204:207], v[20:23]
	v_mfma_f32_16x16x32_bf16 v[16:19], v[188:191], v[204:207], v[16:19]
	v_mfma_f32_16x16x32_bf16 v[12:15], v[178:181], v[212:215], v[12:15]
	v_mfma_f32_16x16x32_bf16 v[8:11], v[188:191], v[212:215], v[8:11]
	v_mfma_f32_16x16x32_bf16 v[4:7], v[178:181], v[220:223], v[4:7]
	v_mfma_f32_16x16x32_bf16 v[0:3], v[188:191], v[220:223], v[0:3]
	v_mfma_f32_16x16x32_bf16 v[28:31], v[184:187], v[200:203], v[28:31]
	v_mfma_f32_16x16x32_bf16 v[24:27], v[192:195], v[200:203], v[24:27]
	v_mfma_f32_16x16x32_bf16 v[20:23], v[184:187], v[208:211], v[20:23]
	v_mfma_f32_16x16x32_bf16 v[16:19], v[192:195], v[208:211], v[16:19]
	v_mfma_f32_16x16x32_bf16 v[12:15], v[184:187], v[216:219], v[12:15]
	v_mfma_f32_16x16x32_bf16 v[8:11], v[192:195], v[216:219], v[8:11]
	v_mfma_f32_16x16x32_bf16 v[4:7], v[184:187], v[224:227], v[4:7]
	v_mfma_f32_16x16x32_bf16 v[0:3], v[192:195], v[224:227], v[0:3]
	s_barrier
	s_setprio 0
	s_add_i32 s56, s56, 2
	s_add_u32 s28, s28, 0x100
	s_addc_u32 s29, s29, 0
	s_add_u32 s54, s54, 0x100
	s_addc_u32 s55, s55, 0
	s_cmp_gt_u32 s56, 29
	s_cbranch_scc0 .LBB0_253
	s_and_b64 vcc, exec, s[16:17]
	s_cbranch_vccz .LBB0_256
	s_barrier

; #define PG8_STAGE(bufoff, gbase, voff) do { _Pragma("unroll") for (int _i = 0; _i < 2; ++_i) \
;         __builtin_amdgcn_global_load_lds((const unsigned*)((const char*)(gbase) + (voff)[_i]), (PG8_LAS unsigned*)(lds + (bufoff) + ldsw + _i * 8192), 16, 0, 0); } while (0)
; #define PG8_LDA(dst, b, h) do { _Pragma("unroll") for (int m = 0; m < 4; ++m) _Pragma("unroll") for (int k = 0; k < 2; ++k) dst[m][k] = *(const PG8_LAS bf16x8*)(lds + PG8_SA(b, h) + aoff + m * 2048 + k * 1024); } while (0)
; #define PG8_LDB(dst, b, h) do { _Pragma("unroll") for (int n = 0; n < 2; ++n) _Pragma("unroll") for (int k = 0; k < 2; ++k) dst[n][k] = *(const PG8_LAS bf16x8*)(lds + PG8_SB(b, h) + boff + n * 2048 + k * 1024); } while (0)
; #define PG8_MMA(ai, bj, At, Bt) do { __builtin_amdgcn_s_setprio(1); _Pragma("unroll") for (int m = 0; m < 4; ++m) _Pragma("unroll") for (int n = 0; n < 2; ++n) _Pragma("unroll") for (int k = 0; k < 2; ++k) \
;         acc[ai][bj][m][n] = __builtin_amdgcn_mfma_f32_16x16x32_bf16(Bt[n][k], At[m][k], acc[ai][bj][m][n], 0, 0, 0); __builtin_amdgcn_s_setprio(0); } while (0)
; #define PG8_WAIT_V(n) asm volatile("s_waitcnt vmcnt(" #n ")" ::: "memory")
; #define PG8_WAIT_L(n) asm volatile("s_waitcnt lgkmcnt(" #n ")" ::: "memory")
; #define PG8_BAR __builtin_amdgcn_s_barrier()
; #define PG8_SCHED __builtin_amdgcn_sched_barrier(0)
; template <class Epi, class Sched, bool ALIGN_EPI = false, bool SP2 = false>
; __device__ __forceinline__ void gemm_phase(PG8_LAS unsigned char* lds, const Gemm g, const Sched& S, const Epi& E) {
;     ...
;             const char* a2 = last ? nA : cA + (size_t)(t + 2) * kstep; const char* b2 = last ? nB : cB + (size_t)(t + 2) * kstep;
;             const char* a3 = a2 + kstep; const char* b3 = b2 + kstep;
;             if (last && has_next) S.a_ready(nxt);
;             if constexpr (SP2) {
;             PG8_LDB(B0, 0, 0); PG8_LDB(B1, 0, 1); PG8_SCHED; PG8_LDA(At, 0, 0); PG8_STAGE(PG8_SA(1, 1), a1 + hstep, voffA);
;             PG8_WAIT_V(8); PG8_WAIT_L(0); PG8_BAR; PG8_MMA(0, 0, At, B0); PG8_MMA(0, 1, At, B1); PG8_BAR; PG8_SCHED;
;             PG8_LDA(At, 0, 1); PG8_STAGE(PG8_SB(0, 0), b2, voffB); PG8_STAGE(PG8_SB(0, 1), b2 + hstep, voffB); PG8_STAGE(PG8_SA(0, 0), a2, voffA);
;             PG8_WAIT_V(8); PG8_WAIT_L(0); PG8_BAR; PG8_MMA(1, 0, At, B0); PG8_MMA(1, 1, At, B1); PG8_BAR; PG8_SCHED;
.LBB0_953:
	v_add_u32_e32 v134, s50, v165
	ds_read_b128 v[144:147], v134
	ds_read_b128 v[148:151], v134 offset:1024
	ds_read_b128 v[170:173], v134 offset:2048
	ds_read_b128 v[174:177], v134 offset:3072
	v_add_u32_e32 v134, s51, v165
	ds_read_b128 v[178:181], v134
	ds_read_b128 v[184:187], v134 offset:1024
	ds_read_b128 v[188:191], v134 offset:2048
	ds_read_b128 v[192:195], v134 offset:3072
	s_add_u32 s34, s30, 0xfff80080
	s_addc_u32 s35, s31, -1
	s_cmp_eq_u32 s57, 28
	s_cselect_b32 s37, s21, s35
	s_cselect_b32 s36, s27, s34
	s_cselect_b32 s35, s19, s56
	s_cselect_b32 s34, s54, s55
	v_lshl_add_u64 v[152:153], s[30:31], 0, v[136:137]
	s_add_i32 m0, s29, 0xc000
	ds_read_b128 v[196:199], v167
	ds_read_b128 v[200:203], v167 offset:1024
	ds_read_b128 v[204:207], v167 offset:2048
	ds_read_b128 v[208:211], v167 offset:3072
	ds_read_b128 v[212:215], v167 offset:4096
	ds_read_b128 v[216:219], v167 offset:5120
	ds_read_b128 v[220:223], v167 offset:6144
	ds_read_b128 v[224:227], v167 offset:7168
	global_load_lds_dwordx4 v[152:153], off
	v_lshl_add_u64 v[152:153], s[30:31], 0, v[138:139]
	s_add_i32 m0, s29, 0xe000
	s_nop 0
	global_load_lds_dwordx4 v[152:153], off
	s_waitcnt vmcnt(8)
	s_waitcnt lgkmcnt(0)
	s_setprio 1
	s_barrier
	s_waitcnt lgkmcnt(0)
	v_mfma_f32_16x16x32_bf16 v[124:127], v[144:147], v[196:199], v[124:127]
	v_mfma_f32_16x16x32_bf16 v[120:123], v[170:173], v[196:199], v[120:123]
	v_mfma_f32_16x16x32_bf16 v[116:119], v[144:147], v[204:207], v[116:119]
	v_mfma_f32_16x16x32_bf16 v[112:115], v[170:173], v[204:207], v[112:115]
	v_mfma_f32_16x16x32_bf16 v[108:111], v[144:147], v[212:215], v[108:111]
	v_mfma_f32_16x16x32_bf16 v[104:107], v[170:173], v[212:215], v[104:107]
	v_mfma_f32_16x16x32_bf16 v[100:103], v[144:147], v[220:223], v[100:103]
	v_mfma_f32_16x16x32_bf16 v[96:99], v[170:173], v[220:223], v[96:99]
	v_mfma_f32_16x16x32_bf16 v[124:127], v[148:151], v[200:203], v[124:127]
	v_mfma_f32_16x16x32_bf16 v[120:123], v[174:177], v[200:203], v[120:123]
	v_mfma_f32_16x16x32_bf16 v[116:119], v[148:151], v[208:211], v[116:119]
	v_mfma_f32_16x16x32_bf16 v[112:115], v[174:177], v[208:211], v[112:115]
	v_mfma_f32_16x16x32_bf16 v[108:111], v[148:151], v[216:219], v[108:111]
	v_mfma_f32_16x16x32_bf16 v[104:107], v[174:177], v[216:219], v[104:107]
	v_mfma_f32_16x16x32_bf16 v[100:103], v[148:151], v[224:227], v[100:103]
	v_mfma_f32_16x16x32_bf16 v[96:99], v[174:177], v[224:227], v[96:99]
	s_setprio 0
	s_setprio 1
	v_mfma_f32_16x16x32_bf16 v[92:95], v[178:181], v[196:199], v[92:95]
	v_mfma_f32_16x16x32_bf16 v[88:91], v[188:191], v[196:199], v[88:91]
	v_mfma_f32_16x16x32_bf16 v[84:87], v[178:181], v[204:207], v[84:87]
	v_mfma_f32_16x16x32_bf16 v[80:83], v[188:191], v[204:207], v[80:83]
	v_mfma_f32_16x16x32_bf16 v[76:79], v[178:181], v[212:215], v[76:79]
	v_mfma_f32_16x16x32_bf16 v[72:75], v[188:191], v[212:215], v[72:75]
	v_mfma_f32_16x16x32_bf16 v[68:71], v[178:181], v[220:223], v[68:71]
	v_mfma_f32_16x16x32_bf16 v[64:67], v[188:191], v[220:223], v[64:67]
	v_mfma_f32_16x16x32_bf16 v[92:95], v[184:187], v[200:203], v[92:95]
	v_mfma_f32_16x16x32_bf16 v[88:91], v[192:195], v[200:203], v[88:91]
	v_mfma_f32_16x16x32_bf16 v[84:87], v[184:187], v[208:211], v[84:87]
	v_mfma_f32_16x16x32_bf16 v[80:83], v[192:195], v[208:211], v[80:83]
	v_mfma_f32_16x16x32_bf16 v[76:79], v[184:187], v[216:219], v[76:79]
	v_mfma_f32_16x16x32_bf16 v[72:75], v[192:195], v[216:219], v[72:75]
	v_mfma_f32_16x16x32_bf16 v[68:71], v[184:187], v[224:227], v[68:71]
	v_mfma_f32_16x16x32_bf16 v[64:67], v[192:195], v[224:227], v[64:67]
	s_barrier
	s_setprio 0
	s_add_i32 s58, s50, s41
	v_lshl_add_u64 v[152:153], s[34:35], 0, v[128:129]
	s_mov_b32 m0, s58
	ds_read_b128 v[196:199], v167 offset:16384
	ds_read_b128 v[200:203], v167 offset:17408
	ds_read_b128 v[204:207], v167 offset:18432
	ds_read_b128 v[208:211], v167 offset:19456
	ds_read_b128 v[212:215], v167 offset:20480
	ds_read_b128 v[216:219], v167 offset:21504
	ds_read_b128 v[220:223], v167 offset:22528
	ds_read_b128 v[224:227], v167 offset:23552
	global_load_lds_dwordx4 v[152:153], off
	s_add_i32 m0, s58, 0x2000
	s_add_u32 s58, s34, 0x80000
	v_lshl_add_u64 v[228:229], s[34:35], 0, v[130:131]
	s_addc_u32 s59, s35, 0
	s_add_i32 s60, s51, s41
	global_load_lds_dwordx4 v[228:229], off
	v_lshl_add_u64 v[230:231], s[58:59], 0, v[128:129]
	s_mov_b32 m0, s60
	v_lshl_add_u64 v[232:233], s[36:37], 0, v[130:131]
	global_load_lds_dwordx4 v[230:231], off
	v_lshl_add_u64 v[230:231], s[58:59], 0, v[130:131]
	s_add_i32 m0, s60, 0x2000
	s_nop 0
	global_load_lds_dwordx4 v[230:231], off
	v_lshl_add_u64 v[230:231], s[36:37], 0, v[128:129]
	s_mov_b32 m0, s29
	s_nop 0
	global_load_lds_dwordx4 v[230:231], off
	s_mov_b32 m0, s42
	s_nop 0
	global_load_lds_dwordx4 v[232:233], off
	s_waitcnt vmcnt(8)
	s_waitcnt lgkmcnt(0)
	s_setprio 1
	s_barrier
; #define PG8_STAGE(bufoff, gbase, voff) do { _Pragma("unroll") for (int _i = 0; _i < 2; ++_i) \
;         __builtin_amdgcn_global_load_lds((const unsigned*)((const char*)(gbase) + (voff)[_i]), (PG8_LAS unsigned*)(lds + (bufoff) + ldsw + _i * 8192), 16, 0, 0); } while (0)
; #define PG8_LDA(dst, b, h) do { _Pragma("unroll") for (int m = 0; m < 4; ++m) _Pragma("unroll") for (int k = 0; k < 2; ++k) dst[m][k] = *(const PG8_LAS bf16x8*)(lds + PG8_SA(b, h) + aoff + m * 2048 + k * 1024); } while (0)
; #define PG8_LDB(dst, b, h) do { _Pragma("unroll") for (int n = 0; n < 2; ++n) _Pragma("unroll") for (int k = 0; k < 2; ++k) dst[n][k] = *(const PG8_LAS bf16x8*)(lds + PG8_SB(b, h) + boff + n * 2048 + k * 1024); } while (0)
; #define PG8_MMA(ai, bj, At, Bt) do { __builtin_amdgcn_s_setprio(1); _Pragma("unroll") for (int m = 0; m < 4; ++m) _Pragma("unroll") for (int n = 0; n < 2; ++n) _Pragma("unroll") for (int k = 0; k < 2; ++k) \
;         acc[ai][bj][m][n] = __builtin_amdgcn_mfma_f32_16x16x32_bf16(Bt[n][k], At[m][k], acc[ai][bj][m][n], 0, 0, 0); __builtin_amdgcn_s_setprio(0); } while (0)
; #define PG8_WAIT_V(n) asm volatile("s_waitcnt vmcnt(" #n ")" ::: "memory")
; #define PG8_WAIT_L(n) asm volatile("s_waitcnt lgkmcnt(" #n ")" ::: "memory")
; #define PG8_BAR __builtin_amdgcn_s_barrier()
; #define PG8_SCHED __builtin_amdgcn_sched_barrier(0)
; template <class Epi, class Sched, bool ALIGN_EPI = false, bool SP2 = false>
; __device__ __forceinline__ void gemm_phase(PG8_LAS unsigned char* lds, const Gemm g, const Sched& S, const Epi& E) {
;     ...
;             PG8_WAIT_V(8); PG8_WAIT_L(0); PG8_BAR; PG8_MMA(1, 0, At, B0); PG8_MMA(1, 1, At, B1); PG8_BAR; PG8_SCHED;
;             PG8_LDB(B0, 1, 0); PG8_LDB(B1, 1, 1); PG8_SCHED; PG8_LDA(At, 1, 0); PG8_STAGE(PG8_SA(0, 1), a2 + hstep, voffA);
;             PG8_WAIT_V(8); PG8_WAIT_L(0); PG8_BAR; PG8_MMA(0, 0, At, B0); PG8_MMA(0, 1, At, B1); PG8_BAR; PG8_SCHED;
	s_waitcnt lgkmcnt(0)
	v_mfma_f32_16x16x32_bf16 v[60:63], v[144:147], v[196:199], v[60:63]
	v_mfma_f32_16x16x32_bf16 v[56:59], v[170:173], v[196:199], v[56:59]
	v_mfma_f32_16x16x32_bf16 v[52:55], v[144:147], v[204:207], v[52:55]
	v_mfma_f32_16x16x32_bf16 v[48:51], v[170:173], v[204:207], v[48:51]
	v_mfma_f32_16x16x32_bf16 v[44:47], v[144:147], v[212:215], v[44:47]
	v_mfma_f32_16x16x32_bf16 v[40:43], v[170:173], v[212:215], v[40:43]
	v_mfma_f32_16x16x32_bf16 v[36:39], v[144:147], v[220:223], v[36:39]
	v_mfma_f32_16x16x32_bf16 v[32:35], v[170:173], v[220:223], v[32:35]
	v_mfma_f32_16x16x32_bf16 v[60:63], v[148:151], v[200:203], v[60:63]
	v_mfma_f32_16x16x32_bf16 v[56:59], v[174:177], v[200:203], v[56:59]
	v_mfma_f32_16x16x32_bf16 v[52:55], v[148:151], v[208:211], v[52:55]
	v_mfma_f32_16x16x32_bf16 v[48:51], v[174:177], v[208:211], v[48:51]
	v_mfma_f32_16x16x32_bf16 v[44:47], v[148:151], v[216:219], v[44:47]
	v_mfma_f32_16x16x32_bf16 v[40:43], v[174:177], v[216:219], v[40:43]
	v_mfma_f32_16x16x32_bf16 v[36:39], v[148:151], v[224:227], v[36:39]
	v_mfma_f32_16x16x32_bf16 v[32:35], v[174:177], v[224:227], v[32:35]
	s_setprio 0
	s_setprio 1
	v_mfma_f32_16x16x32_bf16 v[28:31], v[178:181], v[196:199], v[28:31]
	v_mfma_f32_16x16x32_bf16 v[24:27], v[188:191], v[196:199], v[24:27]
	v_mfma_f32_16x16x32_bf16 v[20:23], v[178:181], v[204:207], v[20:23]
	v_mfma_f32_16x16x32_bf16 v[16:19], v[188:191], v[204:207], v[16:19]
	v_mfma_f32_16x16x32_bf16 v[12:15], v[178:181], v[212:215], v[12:15]
	v_mfma_f32_16x16x32_bf16 v[8:11], v[188:191], v[212:215], v[8:11]
	v_mfma_f32_16x16x32_bf16 v[4:7], v[178:181], v[220:223], v[4:7]
	v_mfma_f32_16x16x32_bf16 v[0:3], v[188:191], v[220:223], v[0:3]
	v_mfma_f32_16x16x32_bf16 v[28:31], v[184:187], v[200:203], v[28:31]
	v_mfma_f32_16x16x32_bf16 v[24:27], v[192:195], v[200:203], v[24:27]
	v_mfma_f32_16x16x32_bf16 v[20:23], v[184:187], v[208:211], v[20:23]
	v_mfma_f32_16x16x32_bf16 v[16:19], v[192:195], v[208:211], v[16:19]
	v_mfma_f32_16x16x32_bf16 v[12:15], v[184:187], v[216:219], v[12:15]
	v_mfma_f32_16x16x32_bf16 v[8:11], v[192:195], v[216:219], v[8:11]
	v_mfma_f32_16x16x32_bf16 v[4:7], v[184:187], v[224:227], v[4:7]
	v_mfma_f32_16x16x32_bf16 v[0:3], v[192:195], v[224:227], v[0:3]
	s_barrier
	s_setprio 0
	s_add_i32 s58, 0, 0x18000
	v_add_u32_e32 v134, s58, v165
	s_add_i32 s59, 0, 0x1c000
	ds_read_b128 v[144:147], v134
	ds_read_b128 v[148:151], v134 offset:1024
	ds_read_b128 v[170:173], v134 offset:2048
	ds_read_b128 v[174:177], v134 offset:3072
	v_add_u32_e32 v134, s59, v165
	ds_read_b128 v[178:181], v134
	ds_read_b128 v[184:187], v134 offset:1024
	ds_read_b128 v[188:191], v134 offset:2048
	ds_read_b128 v[192:195], v134 offset:3072
	s_add_u32 s36, s36, 0x80000
	s_addc_u32 s37, s37, 0
	s_mov_b32 m0, s43
	v_lshl_add_u64 v[234:235], s[36:37], 0, v[128:129]
	ds_read_b128 v[196:199], v167 offset:32768
	ds_read_b128 v[200:203], v167 offset:33792
	ds_read_b128 v[204:207], v167 offset:34816
	ds_read_b128 v[208:211], v167 offset:35840
	ds_read_b128 v[212:215], v167 offset:36864
	ds_read_b128 v[216:219], v167 offset:37888
	ds_read_b128 v[220:223], v167 offset:38912
	ds_read_b128 v[224:227], v167 offset:39936
	global_load_lds_dwordx4 v[234:235], off
	v_lshl_add_u64 v[234:235], s[36:37], 0, v[130:131]
	s_mov_b32 m0, s44
	s_nop 0
	global_load_lds_dwordx4 v[234:235], off
	s_waitcnt vmcnt(8)
	s_waitcnt lgkmcnt(0)
	s_setprio 1
	s_barrier
	s_waitcnt lgkmcnt(0)
	v_mfma_f32_16x16x32_bf16 v[124:127], v[144:147], v[196:199], v[124:127]
	v_mfma_f32_16x16x32_bf16 v[120:123], v[170:173], v[196:199], v[120:123]
	v_mfma_f32_16x16x32_bf16 v[116:119], v[144:147], v[204:207], v[116:119]
	v_mfma_f32_16x16x32_bf16 v[112:115], v[170:173], v[204:207], v[112:115]
	v_mfma_f32_16x16x32_bf16 v[108:111], v[144:147], v[212:215], v[108:111]
	v_mfma_f32_16x16x32_bf16 v[104:107], v[170:173], v[212:215], v[104:107]
	v_mfma_f32_16x16x32_bf16 v[100:103], v[144:147], v[220:223], v[100:103]
	v_mfma_f32_16x16x32_bf16 v[96:99], v[170:173], v[220:223], v[96:99]
	v_mfma_f32_16x16x32_bf16 v[124:127], v[148:151], v[200:203], v[124:127]
	v_mfma_f32_16x16x32_bf16 v[120:123], v[174:177], v[200:203], v[120:123]
	v_mfma_f32_16x16x32_bf16 v[116:119], v[148:151], v[208:211], v[116:119]
	v_mfma_f32_16x16x32_bf16 v[112:115], v[174:177], v[208:211], v[112:115]
	v_mfma_f32_16x16x32_bf16 v[108:111], v[148:151], v[216:219], v[108:111]
	v_mfma_f32_16x16x32_bf16 v[104:107], v[174:177], v[216:219], v[104:107]
	v_mfma_f32_16x16x32_bf16 v[100:103], v[148:151], v[224:227], v[100:103]
	v_mfma_f32_16x16x32_bf16 v[96:99], v[174:177], v[224:227], v[96:99]
	s_setprio 0
	s_setprio 1
	v_mfma_f32_16x16x32_bf16 v[92:95], v[178:181], v[196:199], v[92:95]
	v_mfma_f32_16x16x32_bf16 v[88:91], v[188:191], v[196:199], v[88:91]
	v_mfma_f32_16x16x32_bf16 v[84:87], v[178:181], v[204:207], v[84:87]
	v_mfma_f32_16x16x32_bf16 v[80:83], v[188:191], v[204:207], v[80:83]
	v_mfma_f32_16x16x32_bf16 v[76:79], v[178:181], v[212:215], v[76:79]
	v_mfma_f32_16x16x32_bf16 v[72:75], v[188:191], v[212:215], v[72:75]
	v_mfma_f32_16x16x32_bf16 v[68:71], v[178:181], v[220:223], v[68:71]
	v_mfma_f32_16x16x32_bf16 v[64:67], v[188:191], v[220:223], v[64:67]
	v_mfma_f32_16x16x32_bf16 v[92:95], v[184:187], v[200:203], v[92:95]
	v_mfma_f32_16x16x32_bf16 v[88:91], v[192:195], v[200:203], v[88:91]
	v_mfma_f32_16x16x32_bf16 v[84:87], v[184:187], v[208:211], v[84:87]
	v_mfma_f32_16x16x32_bf16 v[80:83], v[192:195], v[208:211], v[80:83]
	v_mfma_f32_16x16x32_bf16 v[76:79], v[184:187], v[216:219], v[76:79]
	v_mfma_f32_16x16x32_bf16 v[72:75], v[192:195], v[216:219], v[72:75]
	v_mfma_f32_16x16x32_bf16 v[68:71], v[184:187], v[224:227], v[68:71]
	v_mfma_f32_16x16x32_bf16 v[64:67], v[192:195], v[224:227], v[64:67]
	s_barrier
; #define PG8_STAGE(bufoff, gbase, voff) do { _Pragma("unroll") for (int _i = 0; _i < 2; ++_i) \
;         __builtin_amdgcn_global_load_lds((const unsigned*)((const char*)(gbase) + (voff)[_i]), (PG8_LAS unsigned*)(lds + (bufoff) + ldsw + _i * 8192), 16, 0, 0); } while (0)
; #define PG8_LDA(dst, b, h) do { _Pragma("unroll") for (int m = 0; m < 4; ++m) _Pragma("unroll") for (int k = 0; k < 2; ++k) dst[m][k] = *(const PG8_LAS bf16x8*)(lds + PG8_SA(b, h) + aoff + m * 2048 + k * 1024); } while (0)
; #define PG8_MMA(ai, bj, At, Bt) do { __builtin_amdgcn_s_setprio(1); _Pragma("unroll") for (int m = 0; m < 4; ++m) _Pragma("unroll") for (int n = 0; n < 2; ++n) _Pragma("unroll") for (int k = 0; k < 2; ++k) \
;         acc[ai][bj][m][n] = __builtin_amdgcn_mfma_f32_16x16x32_bf16(Bt[n][k], At[m][k], acc[ai][bj][m][n], 0, 0, 0); __builtin_amdgcn_s_setprio(0); } while (0)
; #define PG8_WAIT_V(n) asm volatile("s_waitcnt vmcnt(" #n ")" ::: "memory")
; #define PG8_WAIT_L(n) asm volatile("s_waitcnt lgkmcnt(" #n ")" ::: "memory")
; #define PG8_BAR __builtin_amdgcn_s_barrier()
; #define PG8_SCHED __builtin_amdgcn_sched_barrier(0)
; template <class Epi, class Sched, bool ALIGN_EPI = false, bool SP2 = false>
; __device__ __forceinline__ void gemm_phase(PG8_LAS unsigned char* lds, const Gemm g, const Sched& S, const Epi& E) {
;     ...
;             PG8_LDA(At, 1, 1); PG8_STAGE(PG8_SB(1, 0), b3, voffB); PG8_STAGE(PG8_SB(1, 1), b3 + hstep, voffB); PG8_STAGE(PG8_SA(1, 0), a3, voffA);
;             PG8_WAIT_V(8); PG8_WAIT_L(0); PG8_BAR; PG8_MMA(1, 0, At, B0); PG8_MMA(1, 1, At, B1); PG8_BAR; PG8_SCHED;
	s_setprio 0
	s_add_i32 s36, s58, s41
	v_lshl_add_u64 v[152:153], v[152:153], 0, s[14:15]
	s_mov_b32 m0, s36
	ds_read_b128 v[196:199], v167 offset:49152
	ds_read_b128 v[200:203], v167 offset:50176
	ds_read_b128 v[204:207], v167 offset:51200
	ds_read_b128 v[208:211], v167 offset:52224
	ds_read_b128 v[212:215], v167 offset:53248
	ds_read_b128 v[216:219], v167 offset:54272
	ds_read_b128 v[220:223], v167 offset:55296
	ds_read_b128 v[224:227], v167 offset:56320
	global_load_lds_dwordx4 v[152:153], off
	s_add_i32 m0, s36, 0x2000
	s_add_u32 s34, s34, 0x80080
	v_lshl_add_u64 v[152:153], v[228:229], 0, s[14:15]
	s_addc_u32 s35, s35, 0
	s_add_i32 s36, s59, s41
	global_load_lds_dwordx4 v[152:153], off
	v_lshl_add_u64 v[152:153], s[34:35], 0, v[128:129]
	s_mov_b32 m0, s36
	s_nop 0
	global_load_lds_dwordx4 v[152:153], off
	v_lshl_add_u64 v[152:153], s[34:35], 0, v[130:131]
	s_add_i32 m0, s36, 0x2000
	s_nop 0
	global_load_lds_dwordx4 v[152:153], off
	v_lshl_add_u64 v[152:153], v[230:231], 0, s[14:15]
	s_mov_b32 m0, s45
	s_nop 0
	global_load_lds_dwordx4 v[152:153], off
	v_lshl_add_u64 v[152:153], v[232:233], 0, s[14:15]
	s_mov_b32 m0, s46
	s_nop 0
	global_load_lds_dwordx4 v[152:153], off
	s_waitcnt vmcnt(8)
	s_waitcnt lgkmcnt(0)
	s_setprio 1
	s_barrier
	s_waitcnt lgkmcnt(0)
	v_mfma_f32_16x16x32_bf16 v[60:63], v[144:147], v[196:199], v[60:63]
	v_mfma_f32_16x16x32_bf16 v[56:59], v[170:173], v[196:199], v[56:59]
	v_mfma_f32_16x16x32_bf16 v[52:55], v[144:147], v[204:207], v[52:55]
	v_mfma_f32_16x16x32_bf16 v[48:51], v[170:173], v[204:207], v[48:51]
	v_mfma_f32_16x16x32_bf16 v[44:47], v[144:147], v[212:215], v[44:47]
	v_mfma_f32_16x16x32_bf16 v[40:43], v[170:173], v[212:215], v[40:43]
	v_mfma_f32_16x16x32_bf16 v[36:39], v[144:147], v[220:223], v[36:39]
	v_mfma_f32_16x16x32_bf16 v[32:35], v[170:173], v[220:223], v[32:35]
	v_mfma_f32_16x16x32_bf16 v[60:63], v[148:151], v[200:203], v[60:63]
	v_mfma_f32_16x16x32_bf16 v[56:59], v[174:177], v[200:203], v[56:59]
	v_mfma_f32_16x16x32_bf16 v[52:55], v[148:151], v[208:211], v[52:55]
	v_mfma_f32_16x16x32_bf16 v[48:51], v[174:177], v[208:211], v[48:51]
	v_mfma_f32_16x16x32_bf16 v[44:47], v[148:151], v[216:219], v[44:47]
	v_mfma_f32_16x16x32_bf16 v[40:43], v[174:177], v[216:219], v[40:43]
	v_mfma_f32_16x16x32_bf16 v[36:39], v[148:151], v[224:227], v[36:39]
	v_mfma_f32_16x16x32_bf16 v[32:35], v[174:177], v[224:227], v[32:35]
	s_setprio 0
	s_setprio 1
	v_mfma_f32_16x16x32_bf16 v[28:31], v[178:181], v[196:199], v[28:31]
	v_mfma_f32_16x16x32_bf16 v[24:27], v[188:191], v[196:199], v[24:27]
	v_mfma_f32_16x16x32_bf16 v[20:23], v[178:181], v[204:207], v[20:23]
	v_mfma_f32_16x16x32_bf16 v[16:19], v[188:191], v[204:207], v[16:19]
	v_mfma_f32_16x16x32_bf16 v[12:15], v[178:181], v[212:215], v[12:15]
	v_mfma_f32_16x16x32_bf16 v[8:11], v[188:191], v[212:215], v[8:11]
	v_mfma_f32_16x16x32_bf16 v[4:7], v[178:181], v[220:223], v[4:7]
	v_mfma_f32_16x16x32_bf16 v[0:3], v[188:191], v[220:223], v[0:3]
	v_mfma_f32_16x16x32_bf16 v[28:31], v[184:187], v[200:203], v[28:31]
	v_mfma_f32_16x16x32_bf16 v[24:27], v[192:195], v[200:203], v[24:27]
	v_mfma_f32_16x16x32_bf16 v[20:23], v[184:187], v[208:211], v[20:23]
	v_mfma_f32_16x16x32_bf16 v[16:19], v[192:195], v[208:211], v[16:19]
	v_mfma_f32_16x16x32_bf16 v[12:15], v[184:187], v[216:219], v[12:15]
	v_mfma_f32_16x16x32_bf16 v[8:11], v[192:195], v[216:219], v[8:11]
	v_mfma_f32_16x16x32_bf16 v[4:7], v[184:187], v[224:227], v[4:7]
	v_mfma_f32_16x16x32_bf16 v[0:3], v[192:195], v[224:227], v[0:3]
	s_barrier
	s_setprio 0
	s_add_i32 s57, s57, 2
	s_add_u32 s30, s30, 0x100
	s_addc_u32 s31, s31, 0
	s_add_u32 s55, s55, 0x100
	s_addc_u32 s56, s56, 0
	s_cmp_gt_u32 s57, 29
	s_cbranch_scc0 .LBB0_953
	s_and_b64 vcc, exec, s[16:17]
	s_cbranch_vccz .LBB0_956
	s_barrier

; #define PG8_STAGE(bufoff, gbase, voff) do { _Pragma("unroll") for (int _i = 0; _i < 2; ++_i) \
;         __builtin_amdgcn_global_load_lds((const unsigned*)((const char*)(gbase) + (voff)[_i]), (PG8_LAS unsigned*)(lds + (bufoff) + ldsw + _i * 8192), 16, 0, 0); } while (0)
; #define PG8_LDA(dst, b, h) do { _Pragma("unroll") for (int m = 0; m < 4; ++m) _Pragma("unroll") for (int k = 0; k < 2; ++k) dst[m][k] = *(const PG8_LAS bf16x8*)(lds + PG8_SA(b, h) + aoff + m * 2048 + k * 1024); } while (0)
; #define PG8_LDB(dst, b, h) do { _Pragma("unroll") for (int n = 0; n < 2; ++n) _Pragma("unroll") for (int k = 0; k < 2; ++k) dst[n][k] = *(const PG8_LAS bf16x8*)(lds + PG8_SB(b, h) + boff + n * 2048 + k * 1024); } while (0)
; #define PG8_MMA(ai, bj, At, Bt) do { __builtin_amdgcn_s_setprio(1); _Pragma("unroll") for (int m = 0; m < 4; ++m) _Pragma("unroll") for (int n = 0; n < 2; ++n) _Pragma("unroll") for (int k = 0; k < 2; ++k) \
;         acc[ai][bj][m][n] = __builtin_amdgcn_mfma_f32_16x16x32_bf16(Bt[n][k], At[m][k], acc[ai][bj][m][n], 0, 0, 0); __builtin_amdgcn_s_setprio(0); } while (0)
; #define PG8_WAIT_V(n) asm volatile("s_waitcnt vmcnt(" #n ")" ::: "memory")
; #define PG8_WAIT_L(n) asm volatile("s_waitcnt lgkmcnt(" #n ")" ::: "memory")
; #define PG8_BAR __builtin_amdgcn_s_barrier()
; #define PG8_SCHED __builtin_amdgcn_sched_barrier(0)
; template <class Epi, class Sched, bool ALIGN_EPI = false, bool SP2 = false>
; __device__ __forceinline__ void gemm_phase(PG8_LAS unsigned char* lds, const Gemm g, const Sched& S, const Epi& E) {
;     ...
;             const char* a2 = last ? nA : cA + (size_t)(t + 2) * kstep; const char* b2 = last ? nB : cB + (size_t)(t + 2) * kstep;
;             const char* a3 = a2 + kstep; const char* b3 = b2 + kstep;
;             if (last && has_next) S.a_ready(nxt);
;             if constexpr (SP2) {
;             PG8_LDB(B0, 0, 0); PG8_LDB(B1, 0, 1); PG8_SCHED; PG8_LDA(At, 0, 0); PG8_STAGE(PG8_SA(1, 1), a1 + hstep, voffA);
;             PG8_WAIT_V(8); PG8_WAIT_L(0); PG8_BAR; PG8_MMA(0, 0, At, B0); PG8_MMA(0, 1, At, B1); PG8_BAR; PG8_SCHED;
;             PG8_LDA(At, 0, 1); PG8_STAGE(PG8_SB(0, 0), b2, voffB); PG8_STAGE(PG8_SB(0, 1), b2 + hstep, voffB); PG8_STAGE(PG8_SA(0, 0), a2, voffA);
;             PG8_WAIT_V(8); PG8_WAIT_L(0); PG8_BAR; PG8_MMA(1, 0, At, B0); PG8_MMA(1, 1, At, B1); PG8_BAR; PG8_SCHED;
.LBB0_1071:
	ds_read_b128 v[148:151], v162
	ds_read_b128 v[170:173], v162 offset:1024
	ds_read_b128 v[174:177], v162 offset:2048
	ds_read_b128 v[178:181], v162 offset:3072
	ds_read_b128 v[184:187], v163
	ds_read_b128 v[188:191], v163 offset:1024
	ds_read_b128 v[192:195], v163 offset:2048
	ds_read_b128 v[196:199], v163 offset:3072
	s_add_u32 s34, s30, 0xfff80080
	s_addc_u32 s35, s31, -1
	s_cmp_eq_u32 s58, 28
	s_cselect_b32 s37, s21, s35
	s_cselect_b32 s36, s29, s34
	s_cselect_b32 s35, s19, s57
	s_cselect_b32 s34, s55, s56
	v_lshl_add_u64 v[152:153], s[30:31], 0, v[140:141]
	s_add_i32 m0, s27, 0xc000
	ds_read_b128 v[200:203], v164
	ds_read_b128 v[204:207], v164 offset:1024
	ds_read_b128 v[208:211], v164 offset:2048
	ds_read_b128 v[212:215], v164 offset:3072
	ds_read_b128 v[216:219], v164 offset:4096
	ds_read_b128 v[220:223], v164 offset:5120
	ds_read_b128 v[224:227], v164 offset:6144
	ds_read_b128 v[228:231], v164 offset:7168
	global_load_lds_dwordx4 v[152:153], off
	v_lshl_add_u64 v[152:153], s[30:31], 0, v[142:143]
	s_add_i32 m0, s27, 0xe000
	s_nop 0
	global_load_lds_dwordx4 v[152:153], off
	s_waitcnt vmcnt(8)
	s_waitcnt lgkmcnt(0)
	s_setprio 1
	s_barrier
	s_waitcnt lgkmcnt(0)
	v_mfma_f32_16x16x32_bf16 v[124:127], v[148:151], v[200:203], v[124:127]
	v_mfma_f32_16x16x32_bf16 v[120:123], v[174:177], v[200:203], v[120:123]
	v_mfma_f32_16x16x32_bf16 v[116:119], v[148:151], v[208:211], v[116:119]
	v_mfma_f32_16x16x32_bf16 v[112:115], v[174:177], v[208:211], v[112:115]
	v_mfma_f32_16x16x32_bf16 v[108:111], v[148:151], v[216:219], v[108:111]
	v_mfma_f32_16x16x32_bf16 v[104:107], v[174:177], v[216:219], v[104:107]
	v_mfma_f32_16x16x32_bf16 v[100:103], v[148:151], v[224:227], v[100:103]
	v_mfma_f32_16x16x32_bf16 v[96:99], v[174:177], v[224:227], v[96:99]
	v_mfma_f32_16x16x32_bf16 v[124:127], v[170:173], v[204:207], v[124:127]
	v_mfma_f32_16x16x32_bf16 v[120:123], v[178:181], v[204:207], v[120:123]
	v_mfma_f32_16x16x32_bf16 v[116:119], v[170:173], v[212:215], v[116:119]
	v_mfma_f32_16x16x32_bf16 v[112:115], v[178:181], v[212:215], v[112:115]
	v_mfma_f32_16x16x32_bf16 v[108:111], v[170:173], v[220:223], v[108:111]
	v_mfma_f32_16x16x32_bf16 v[104:107], v[178:181], v[220:223], v[104:107]
	v_mfma_f32_16x16x32_bf16 v[100:103], v[170:173], v[228:231], v[100:103]
	v_mfma_f32_16x16x32_bf16 v[96:99], v[178:181], v[228:231], v[96:99]
	s_setprio 0
	s_setprio 1
	v_mfma_f32_16x16x32_bf16 v[92:95], v[184:187], v[200:203], v[92:95]
	v_mfma_f32_16x16x32_bf16 v[88:91], v[192:195], v[200:203], v[88:91]
	v_mfma_f32_16x16x32_bf16 v[84:87], v[184:187], v[208:211], v[84:87]
	v_mfma_f32_16x16x32_bf16 v[80:83], v[192:195], v[208:211], v[80:83]
	v_mfma_f32_16x16x32_bf16 v[76:79], v[184:187], v[216:219], v[76:79]
	v_mfma_f32_16x16x32_bf16 v[72:75], v[192:195], v[216:219], v[72:75]
	v_mfma_f32_16x16x32_bf16 v[68:71], v[184:187], v[224:227], v[68:71]
	v_mfma_f32_16x16x32_bf16 v[64:67], v[192:195], v[224:227], v[64:67]
	v_mfma_f32_16x16x32_bf16 v[92:95], v[188:191], v[204:207], v[92:95]
	v_mfma_f32_16x16x32_bf16 v[88:91], v[196:199], v[204:207], v[88:91]
	v_mfma_f32_16x16x32_bf16 v[84:87], v[188:191], v[212:215], v[84:87]
	v_mfma_f32_16x16x32_bf16 v[80:83], v[196:199], v[212:215], v[80:83]
	v_mfma_f32_16x16x32_bf16 v[76:79], v[188:191], v[220:223], v[76:79]
	v_mfma_f32_16x16x32_bf16 v[72:75], v[196:199], v[220:223], v[72:75]
	v_mfma_f32_16x16x32_bf16 v[68:71], v[188:191], v[228:231], v[68:71]
	v_mfma_f32_16x16x32_bf16 v[64:67], v[196:199], v[228:231], v[64:67]
	s_barrier
	s_setprio 0
	s_add_i32 s59, s52, s33
	v_lshl_add_u64 v[152:153], s[34:35], 0, v[130:131]
	s_mov_b32 m0, s59
	ds_read_b128 v[200:203], v164 offset:16384
	ds_read_b128 v[204:207], v164 offset:17408
	ds_read_b128 v[208:211], v164 offset:18432
	ds_read_b128 v[212:215], v164 offset:19456
	ds_read_b128 v[216:219], v164 offset:20480
	ds_read_b128 v[220:223], v164 offset:21504
	ds_read_b128 v[224:227], v164 offset:22528
	ds_read_b128 v[228:231], v164 offset:23552
	global_load_lds_dwordx4 v[152:153], off
	s_add_i32 m0, s59, 0x2000
	s_add_u32 s60, s34, 0x80000
	v_lshl_add_u64 v[232:233], s[34:35], 0, v[134:135]
	s_addc_u32 s61, s35, 0
	s_add_i32 s59, s53, s33
	global_load_lds_dwordx4 v[232:233], off
	v_lshl_add_u64 v[234:235], s[60:61], 0, v[130:131]
	s_mov_b32 m0, s59
	v_lshl_add_u64 v[236:237], s[36:37], 0, v[132:133]
	global_load_lds_dwordx4 v[234:235], off
	v_lshl_add_u64 v[234:235], s[60:61], 0, v[134:135]
	s_add_i32 m0, s59, 0x2000
	s_nop 0
	global_load_lds_dwordx4 v[234:235], off
	v_lshl_add_u64 v[234:235], s[36:37], 0, v[128:129]
	s_mov_b32 m0, s27
	s_nop 0
	global_load_lds_dwordx4 v[234:235], off
	s_mov_b32 m0, s42
	s_nop 0
	global_load_lds_dwordx4 v[236:237], off
	s_waitcnt vmcnt(8)
	s_waitcnt lgkmcnt(0)
	s_setprio 1
	s_barrier
; #define PG8_STAGE(bufoff, gbase, voff) do { _Pragma("unroll") for (int _i = 0; _i < 2; ++_i) \
;         __builtin_amdgcn_global_load_lds((const unsigned*)((const char*)(gbase) + (voff)[_i]), (PG8_LAS unsigned*)(lds + (bufoff) + ldsw + _i * 8192), 16, 0, 0); } while (0)
; #define PG8_LDA(dst, b, h) do { _Pragma("unroll") for (int m = 0; m < 4; ++m) _Pragma("unroll") for (int k = 0; k < 2; ++k) dst[m][k] = *(const PG8_LAS bf16x8*)(lds + PG8_SA(b, h) + aoff + m * 2048 + k * 1024); } while (0)
; #define PG8_LDB(dst, b, h) do { _Pragma("unroll") for (int n = 0; n < 2; ++n) _Pragma("unroll") for (int k = 0; k < 2; ++k) dst[n][k] = *(const PG8_LAS bf16x8*)(lds + PG8_SB(b, h) + boff + n * 2048 + k * 1024); } while (0)
; #define PG8_MMA(ai, bj, At, Bt) do { __builtin_amdgcn_s_setprio(1); _Pragma("unroll") for (int m = 0; m < 4; ++m) _Pragma("unroll") for (int n = 0; n < 2; ++n) _Pragma("unroll") for (int k = 0; k < 2; ++k) \
;         acc[ai][bj][m][n] = __builtin_amdgcn_mfma_f32_16x16x32_bf16(Bt[n][k], At[m][k], acc[ai][bj][m][n], 0, 0, 0); __builtin_amdgcn_s_setprio(0); } while (0)
; #define PG8_WAIT_V(n) asm volatile("s_waitcnt vmcnt(" #n ")" ::: "memory")
; #define PG8_WAIT_L(n) asm volatile("s_waitcnt lgkmcnt(" #n ")" ::: "memory")
; #define PG8_BAR __builtin_amdgcn_s_barrier()
; #define PG8_SCHED __builtin_amdgcn_sched_barrier(0)
; template <class Epi, class Sched, bool ALIGN_EPI = false, bool SP2 = false>
; __device__ __forceinline__ void gemm_phase(PG8_LAS unsigned char* lds, const Gemm g, const Sched& S, const Epi& E) {
;     ...
;             PG8_WAIT_V(8); PG8_WAIT_L(0); PG8_BAR; PG8_MMA(1, 0, At, B0); PG8_MMA(1, 1, At, B1); PG8_BAR; PG8_SCHED;
;             PG8_LDB(B0, 1, 0); PG8_LDB(B1, 1, 1); PG8_SCHED; PG8_LDA(At, 1, 0); PG8_STAGE(PG8_SA(0, 1), a2 + hstep, voffA);
;             PG8_WAIT_V(8); PG8_WAIT_L(0); PG8_BAR; PG8_MMA(0, 0, At, B0); PG8_MMA(0, 1, At, B1); PG8_BAR; PG8_SCHED;
	s_waitcnt lgkmcnt(0)
	v_mfma_f32_16x16x32_bf16 v[60:63], v[148:151], v[200:203], v[60:63]
	v_mfma_f32_16x16x32_bf16 v[56:59], v[174:177], v[200:203], v[56:59]
	v_mfma_f32_16x16x32_bf16 v[52:55], v[148:151], v[208:211], v[52:55]
	v_mfma_f32_16x16x32_bf16 v[48:51], v[174:177], v[208:211], v[48:51]
	v_mfma_f32_16x16x32_bf16 v[44:47], v[148:151], v[216:219], v[44:47]
	v_mfma_f32_16x16x32_bf16 v[40:43], v[174:177], v[216:219], v[40:43]
	v_mfma_f32_16x16x32_bf16 v[36:39], v[148:151], v[224:227], v[36:39]
	v_mfma_f32_16x16x32_bf16 v[32:35], v[174:177], v[224:227], v[32:35]
	v_mfma_f32_16x16x32_bf16 v[60:63], v[170:173], v[204:207], v[60:63]
	v_mfma_f32_16x16x32_bf16 v[56:59], v[178:181], v[204:207], v[56:59]
	v_mfma_f32_16x16x32_bf16 v[52:55], v[170:173], v[212:215], v[52:55]
	v_mfma_f32_16x16x32_bf16 v[48:51], v[178:181], v[212:215], v[48:51]
	v_mfma_f32_16x16x32_bf16 v[44:47], v[170:173], v[220:223], v[44:47]
	v_mfma_f32_16x16x32_bf16 v[40:43], v[178:181], v[220:223], v[40:43]
	v_mfma_f32_16x16x32_bf16 v[36:39], v[170:173], v[228:231], v[36:39]
	v_mfma_f32_16x16x32_bf16 v[32:35], v[178:181], v[228:231], v[32:35]
	s_setprio 0
	s_setprio 1
	v_mfma_f32_16x16x32_bf16 v[28:31], v[184:187], v[200:203], v[28:31]
	v_mfma_f32_16x16x32_bf16 v[24:27], v[192:195], v[200:203], v[24:27]
	v_mfma_f32_16x16x32_bf16 v[20:23], v[184:187], v[208:211], v[20:23]
	v_mfma_f32_16x16x32_bf16 v[16:19], v[192:195], v[208:211], v[16:19]
	v_mfma_f32_16x16x32_bf16 v[12:15], v[184:187], v[216:219], v[12:15]
	v_mfma_f32_16x16x32_bf16 v[8:11], v[192:195], v[216:219], v[8:11]
	v_mfma_f32_16x16x32_bf16 v[4:7], v[184:187], v[224:227], v[4:7]
	v_mfma_f32_16x16x32_bf16 v[0:3], v[192:195], v[224:227], v[0:3]
	v_mfma_f32_16x16x32_bf16 v[28:31], v[188:191], v[204:207], v[28:31]
	v_mfma_f32_16x16x32_bf16 v[24:27], v[196:199], v[204:207], v[24:27]
	v_mfma_f32_16x16x32_bf16 v[20:23], v[188:191], v[212:215], v[20:23]
	v_mfma_f32_16x16x32_bf16 v[16:19], v[196:199], v[212:215], v[16:19]
	v_mfma_f32_16x16x32_bf16 v[12:15], v[188:191], v[220:223], v[12:15]
	v_mfma_f32_16x16x32_bf16 v[8:11], v[196:199], v[220:223], v[8:11]
	v_mfma_f32_16x16x32_bf16 v[4:7], v[188:191], v[228:231], v[4:7]
	v_mfma_f32_16x16x32_bf16 v[0:3], v[196:199], v[228:231], v[0:3]
	s_barrier
	s_setprio 0
	s_add_i32 s59, 0, 0x18000
	v_add_u32_e32 v136, s59, v160
	s_add_i32 s60, 0, 0x1c000
	ds_read_b128 v[148:151], v136
	ds_read_b128 v[170:173], v136 offset:1024
	ds_read_b128 v[174:177], v136 offset:2048
	ds_read_b128 v[178:181], v136 offset:3072
	v_add_u32_e32 v136, s60, v160
	ds_read_b128 v[184:187], v136
	ds_read_b128 v[188:191], v136 offset:1024
	ds_read_b128 v[192:195], v136 offset:2048
	ds_read_b128 v[196:199], v136 offset:3072
	s_add_u32 s36, s36, 0x80000
	s_addc_u32 s37, s37, 0
	s_mov_b32 m0, s43
	v_lshl_add_u64 v[238:239], s[36:37], 0, v[128:129]
	ds_read_b128 v[200:203], v164 offset:32768
	ds_read_b128 v[204:207], v164 offset:33792
	ds_read_b128 v[208:211], v164 offset:34816
	ds_read_b128 v[212:215], v164 offset:35840
	ds_read_b128 v[216:219], v164 offset:36864
	ds_read_b128 v[220:223], v164 offset:37888
	ds_read_b128 v[224:227], v164 offset:38912
	ds_read_b128 v[228:231], v164 offset:39936
	global_load_lds_dwordx4 v[238:239], off
	v_lshl_add_u64 v[238:239], s[36:37], 0, v[132:133]
	s_mov_b32 m0, s44
	s_nop 0
	global_load_lds_dwordx4 v[238:239], off
	s_waitcnt vmcnt(8)
	s_waitcnt lgkmcnt(0)
	s_setprio 1
	s_barrier
	s_waitcnt lgkmcnt(0)
	v_mfma_f32_16x16x32_bf16 v[124:127], v[148:151], v[200:203], v[124:127]
	v_mfma_f32_16x16x32_bf16 v[120:123], v[174:177], v[200:203], v[120:123]
	v_mfma_f32_16x16x32_bf16 v[116:119], v[148:151], v[208:211], v[116:119]
	v_mfma_f32_16x16x32_bf16 v[112:115], v[174:177], v[208:211], v[112:115]
	v_mfma_f32_16x16x32_bf16 v[108:111], v[148:151], v[216:219], v[108:111]
	v_mfma_f32_16x16x32_bf16 v[104:107], v[174:177], v[216:219], v[104:107]
	v_mfma_f32_16x16x32_bf16 v[100:103], v[148:151], v[224:227], v[100:103]
	v_mfma_f32_16x16x32_bf16 v[96:99], v[174:177], v[224:227], v[96:99]
	v_mfma_f32_16x16x32_bf16 v[124:127], v[170:173], v[204:207], v[124:127]
	v_mfma_f32_16x16x32_bf16 v[120:123], v[178:181], v[204:207], v[120:123]
	v_mfma_f32_16x16x32_bf16 v[116:119], v[170:173], v[212:215], v[116:119]
	v_mfma_f32_16x16x32_bf16 v[112:115], v[178:181], v[212:215], v[112:115]
	v_mfma_f32_16x16x32_bf16 v[108:111], v[170:173], v[220:223], v[108:111]
	v_mfma_f32_16x16x32_bf16 v[104:107], v[178:181], v[220:223], v[104:107]
	v_mfma_f32_16x16x32_bf16 v[100:103], v[170:173], v[228:231], v[100:103]
	v_mfma_f32_16x16x32_bf16 v[96:99], v[178:181], v[228:231], v[96:99]
	s_setprio 0
	s_setprio 1
	v_mfma_f32_16x16x32_bf16 v[92:95], v[184:187], v[200:203], v[92:95]
	v_mfma_f32_16x16x32_bf16 v[88:91], v[192:195], v[200:203], v[88:91]
	v_mfma_f32_16x16x32_bf16 v[84:87], v[184:187], v[208:211], v[84:87]
	v_mfma_f32_16x16x32_bf16 v[80:83], v[192:195], v[208:211], v[80:83]
	v_mfma_f32_16x16x32_bf16 v[76:79], v[184:187], v[216:219], v[76:79]
	v_mfma_f32_16x16x32_bf16 v[72:75], v[192:195], v[216:219], v[72:75]
	v_mfma_f32_16x16x32_bf16 v[68:71], v[184:187], v[224:227], v[68:71]
	v_mfma_f32_16x16x32_bf16 v[64:67], v[192:195], v[224:227], v[64:67]
	v_mfma_f32_16x16x32_bf16 v[92:95], v[188:191], v[204:207], v[92:95]
	v_mfma_f32_16x16x32_bf16 v[88:91], v[196:199], v[204:207], v[88:91]
	v_mfma_f32_16x16x32_bf16 v[84:87], v[188:191], v[212:215], v[84:87]
	v_mfma_f32_16x16x32_bf16 v[80:83], v[196:199], v[212:215], v[80:83]
	v_mfma_f32_16x16x32_bf16 v[76:79], v[188:191], v[220:223], v[76:79]
	v_mfma_f32_16x16x32_bf16 v[72:75], v[196:199], v[220:223], v[72:75]
	v_mfma_f32_16x16x32_bf16 v[68:71], v[188:191], v[228:231], v[68:71]
	v_mfma_f32_16x16x32_bf16 v[64:67], v[196:199], v[228:231], v[64:67]
	s_barrier
; #define PG8_STAGE(bufoff, gbase, voff) do { _Pragma("unroll") for (int _i = 0; _i < 2; ++_i) \
;         __builtin_amdgcn_global_load_lds((const unsigned*)((const char*)(gbase) + (voff)[_i]), (PG8_LAS unsigned*)(lds + (bufoff) + ldsw + _i * 8192), 16, 0, 0); } while (0)
; #define PG8_LDA(dst, b, h) do { _Pragma("unroll") for (int m = 0; m < 4; ++m) _Pragma("unroll") for (int k = 0; k < 2; ++k) dst[m][k] = *(const PG8_LAS bf16x8*)(lds + PG8_SA(b, h) + aoff + m * 2048 + k * 1024); } while (0)
; #define PG8_MMA(ai, bj, At, Bt) do { __builtin_amdgcn_s_setprio(1); _Pragma("unroll") for (int m = 0; m < 4; ++m) _Pragma("unroll") for (int n = 0; n < 2; ++n) _Pragma("unroll") for (int k = 0; k < 2; ++k) \
;         acc[ai][bj][m][n] = __builtin_amdgcn_mfma_f32_16x16x32_bf16(Bt[n][k], At[m][k], acc[ai][bj][m][n], 0, 0, 0); __builtin_amdgcn_s_setprio(0); } while (0)
; #define PG8_WAIT_V(n) asm volatile("s_waitcnt vmcnt(" #n ")" ::: "memory")
; #define PG8_WAIT_L(n) asm volatile("s_waitcnt lgkmcnt(" #n ")" ::: "memory")
; #define PG8_BAR __builtin_amdgcn_s_barrier()
; #define PG8_SCHED __builtin_amdgcn_sched_barrier(0)
; template <class Epi, class Sched, bool ALIGN_EPI = false, bool SP2 = false>
; __device__ __forceinline__ void gemm_phase(PG8_LAS unsigned char* lds, const Gemm g, const Sched& S, const Epi& E) {
;     ...
;             PG8_LDA(At, 1, 1); PG8_STAGE(PG8_SB(1, 0), b3, voffB); PG8_STAGE(PG8_SB(1, 1), b3 + hstep, voffB); PG8_STAGE(PG8_SA(1, 0), a3, voffA);
;             PG8_WAIT_V(8); PG8_WAIT_L(0); PG8_BAR; PG8_MMA(1, 0, At, B0); PG8_MMA(1, 1, At, B1); PG8_BAR; PG8_SCHED;
	s_setprio 0
	s_add_i32 s36, s59, s33
	v_lshl_add_u64 v[152:153], v[152:153], 0, s[14:15]
	s_mov_b32 m0, s36
	ds_read_b128 v[200:203], v164 offset:49152
	ds_read_b128 v[204:207], v164 offset:50176
	ds_read_b128 v[208:211], v164 offset:51200
	ds_read_b128 v[212:215], v164 offset:52224
	ds_read_b128 v[216:219], v164 offset:53248
	ds_read_b128 v[220:223], v164 offset:54272
	ds_read_b128 v[224:227], v164 offset:55296
	ds_read_b128 v[228:231], v164 offset:56320
	global_load_lds_dwordx4 v[152:153], off
	s_add_i32 m0, s36, 0x2000
	s_add_u32 s34, s34, 0x80080
	v_lshl_add_u64 v[152:153], v[232:233], 0, s[14:15]
	s_addc_u32 s35, s35, 0
	s_add_i32 s36, s60, s33
	global_load_lds_dwordx4 v[152:153], off
	v_lshl_add_u64 v[152:153], s[34:35], 0, v[130:131]
	s_mov_b32 m0, s36
	s_nop 0
	global_load_lds_dwordx4 v[152:153], off
	v_lshl_add_u64 v[152:153], s[34:35], 0, v[134:135]
	s_add_i32 m0, s36, 0x2000
	s_nop 0
	global_load_lds_dwordx4 v[152:153], off
	v_lshl_add_u64 v[152:153], v[234:235], 0, s[14:15]
	s_mov_b32 m0, s46
	s_nop 0
	global_load_lds_dwordx4 v[152:153], off
	v_lshl_add_u64 v[152:153], v[236:237], 0, s[14:15]
	s_mov_b32 m0, s47
	s_nop 0
	global_load_lds_dwordx4 v[152:153], off
	s_waitcnt vmcnt(8)
	s_waitcnt lgkmcnt(0)
	s_setprio 1
	s_barrier
	s_waitcnt lgkmcnt(0)
	v_mfma_f32_16x16x32_bf16 v[60:63], v[148:151], v[200:203], v[60:63]
	v_mfma_f32_16x16x32_bf16 v[56:59], v[174:177], v[200:203], v[56:59]
	v_mfma_f32_16x16x32_bf16 v[52:55], v[148:151], v[208:211], v[52:55]
	v_mfma_f32_16x16x32_bf16 v[48:51], v[174:177], v[208:211], v[48:51]
	v_mfma_f32_16x16x32_bf16 v[44:47], v[148:151], v[216:219], v[44:47]
	v_mfma_f32_16x16x32_bf16 v[40:43], v[174:177], v[216:219], v[40:43]
	v_mfma_f32_16x16x32_bf16 v[36:39], v[148:151], v[224:227], v[36:39]
	v_mfma_f32_16x16x32_bf16 v[32:35], v[174:177], v[224:227], v[32:35]
	v_mfma_f32_16x16x32_bf16 v[60:63], v[170:173], v[204:207], v[60:63]
	v_mfma_f32_16x16x32_bf16 v[56:59], v[178:181], v[204:207], v[56:59]
	v_mfma_f32_16x16x32_bf16 v[52:55], v[170:173], v[212:215], v[52:55]
	v_mfma_f32_16x16x32_bf16 v[48:51], v[178:181], v[212:215], v[48:51]
	v_mfma_f32_16x16x32_bf16 v[44:47], v[170:173], v[220:223], v[44:47]
	v_mfma_f32_16x16x32_bf16 v[40:43], v[178:181], v[220:223], v[40:43]
	v_mfma_f32_16x16x32_bf16 v[36:39], v[170:173], v[228:231], v[36:39]
	v_mfma_f32_16x16x32_bf16 v[32:35], v[178:181], v[228:231], v[32:35]
	s_setprio 0
	s_setprio 1
	v_mfma_f32_16x16x32_bf16 v[28:31], v[184:187], v[200:203], v[28:31]
	v_mfma_f32_16x16x32_bf16 v[24:27], v[192:195], v[200:203], v[24:27]
	v_mfma_f32_16x16x32_bf16 v[20:23], v[184:187], v[208:211], v[20:23]
	v_mfma_f32_16x16x32_bf16 v[16:19], v[192:195], v[208:211], v[16:19]
	v_mfma_f32_16x16x32_bf16 v[12:15], v[184:187], v[216:219], v[12:15]
	v_mfma_f32_16x16x32_bf16 v[8:11], v[192:195], v[216:219], v[8:11]
	v_mfma_f32_16x16x32_bf16 v[4:7], v[184:187], v[224:227], v[4:7]
	v_mfma_f32_16x16x32_bf16 v[0:3], v[192:195], v[224:227], v[0:3]
	v_mfma_f32_16x16x32_bf16 v[28:31], v[188:191], v[204:207], v[28:31]
	v_mfma_f32_16x16x32_bf16 v[24:27], v[196:199], v[204:207], v[24:27]
	v_mfma_f32_16x16x32_bf16 v[20:23], v[188:191], v[212:215], v[20:23]
	v_mfma_f32_16x16x32_bf16 v[16:19], v[196:199], v[212:215], v[16:19]
	v_mfma_f32_16x16x32_bf16 v[12:15], v[188:191], v[220:223], v[12:15]
	v_mfma_f32_16x16x32_bf16 v[8:11], v[196:199], v[220:223], v[8:11]
	v_mfma_f32_16x16x32_bf16 v[4:7], v[188:191], v[228:231], v[4:7]
	v_mfma_f32_16x16x32_bf16 v[0:3], v[196:199], v[228:231], v[0:3]
	s_barrier
	s_setprio 0
	s_add_i32 s58, s58, 2
	s_add_u32 s30, s30, 0x100
	s_addc_u32 s31, s31, 0
	s_add_u32 s56, s56, 0x100
	s_addc_u32 s57, s57, 0
	s_cmp_gt_u32 s58, 29
	s_cbranch_scc0 .LBB0_1071
	s_and_b64 vcc, exec, s[16:17]
	s_cbranch_vccz .LBB0_1074
	s_barrier

; #define PG8_STAGE(bufoff, gbase, voff) do { _Pragma("unroll") for (int _i = 0; _i < 2; ++_i) \
;         __builtin_amdgcn_global_load_lds((const unsigned*)((const char*)(gbase) + (voff)[_i]), (PG8_LAS unsigned*)(lds + (bufoff) + ldsw + _i * 8192), 16, 0, 0); } while (0)
; #define PG8_LDA(dst, b, h) do { _Pragma("unroll") for (int m = 0; m < 4; ++m) _Pragma("unroll") for (int k = 0; k < 2; ++k) dst[m][k] = *(const PG8_LAS bf16x8*)(lds + PG8_SA(b, h) + aoff + m * 2048 + k * 1024); } while (0)
; #define PG8_LDB(dst, b, h) do { _Pragma("unroll") for (int n = 0; n < 2; ++n) _Pragma("unroll") for (int k = 0; k < 2; ++k) dst[n][k] = *(const PG8_LAS bf16x8*)(lds + PG8_SB(b, h) + boff + n * 2048 + k * 1024); } while (0)
; #define PG8_MMA(ai, bj, At, Bt) do { __builtin_amdgcn_s_setprio(1); _Pragma("unroll") for (int m = 0; m < 4; ++m) _Pragma("unroll") for (int n = 0; n < 2; ++n) _Pragma("unroll") for (int k = 0; k < 2; ++k) \
;         acc[ai][bj][m][n] = __builtin_amdgcn_mfma_f32_16x16x32_bf16(Bt[n][k], At[m][k], acc[ai][bj][m][n], 0, 0, 0); __builtin_amdgcn_s_setprio(0); } while (0)
; #define PG8_WAIT_V(n) asm volatile("s_waitcnt vmcnt(" #n ")" ::: "memory")
; #define PG8_WAIT_L(n) asm volatile("s_waitcnt lgkmcnt(" #n ")" ::: "memory")
; #define PG8_BAR __builtin_amdgcn_s_barrier()
; #define PG8_SCHED __builtin_amdgcn_sched_barrier(0)
; template <class Epi, class Sched, bool ALIGN_EPI = false, bool SP2 = false>
; __device__ __forceinline__ void gemm_phase(PG8_LAS unsigned char* lds, const Gemm g, const Sched& S, const Epi& E) {
;     ...
;             const char* a2 = last ? nA : cA + (size_t)(t + 2) * kstep; const char* b2 = last ? nB : cB + (size_t)(t + 2) * kstep;
;             const char* a3 = a2 + kstep; const char* b3 = b2 + kstep;
;             if (last && has_next) S.a_ready(nxt);
;             if constexpr (SP2) {
;             PG8_LDB(B0, 0, 0); PG8_LDB(B1, 0, 1); PG8_SCHED; PG8_LDA(At, 0, 0); PG8_STAGE(PG8_SA(1, 1), a1 + hstep, voffA);
;             PG8_WAIT_V(8); PG8_WAIT_L(0); PG8_BAR; PG8_MMA(0, 0, At, B0); PG8_MMA(0, 1, At, B1); PG8_BAR; PG8_SCHED;
;             PG8_LDA(At, 0, 1); PG8_STAGE(PG8_SB(0, 0), b2, voffB); PG8_STAGE(PG8_SB(0, 1), b2 + hstep, voffB); PG8_STAGE(PG8_SA(0, 0), a2, voffA);
;             PG8_WAIT_V(8); PG8_WAIT_L(0); PG8_BAR; PG8_MMA(1, 0, At, B0); PG8_MMA(1, 1, At, B1); PG8_BAR; PG8_SCHED;
.LBB0_1343:
	v_add_u32_e32 v134, s46, v161
	ds_read_b128 v[144:147], v134
	ds_read_b128 v[166:169], v134 offset:1024
	ds_read_b128 v[170:173], v134 offset:2048
	ds_read_b128 v[174:177], v134 offset:3072
	v_add_u32_e32 v134, s47, v161
	ds_read_b128 v[178:181], v134
	ds_read_b128 v[184:187], v134 offset:1024
	ds_read_b128 v[188:191], v134 offset:2048
	ds_read_b128 v[192:195], v134 offset:3072
	s_add_u32 s34, s30, 0xfff00080
	s_addc_u32 s35, s31, -1
	s_cmp_eq_u32 s56, 60
	s_cselect_b32 s37, s21, s35
	s_cselect_b32 s36, s27, s34
	s_cselect_b32 s35, s19, s55
	s_cselect_b32 s34, s49, s54
	v_lshl_add_u64 v[148:149], s[30:31], 0, v[136:137]
	s_add_i32 m0, s29, 0xc000
	ds_read_b128 v[196:199], v163
	ds_read_b128 v[200:203], v163 offset:1024
	ds_read_b128 v[204:207], v163 offset:2048
	ds_read_b128 v[208:211], v163 offset:3072
	ds_read_b128 v[212:215], v163 offset:4096
	ds_read_b128 v[216:219], v163 offset:5120
	ds_read_b128 v[220:223], v163 offset:6144
	ds_read_b128 v[224:227], v163 offset:7168
	global_load_lds_dwordx4 v[148:149], off
	v_lshl_add_u64 v[148:149], s[30:31], 0, v[138:139]
	s_add_i32 m0, s29, 0xe000
	s_nop 0
	global_load_lds_dwordx4 v[148:149], off
	s_waitcnt vmcnt(8)
	s_waitcnt lgkmcnt(0)
	s_setprio 1
	s_barrier
	s_waitcnt lgkmcnt(0)
	v_mfma_f32_16x16x32_bf16 v[120:123], v[144:147], v[196:199], v[120:123]
	v_mfma_f32_16x16x32_bf16 v[124:127], v[170:173], v[196:199], v[124:127]
	v_mfma_f32_16x16x32_bf16 v[112:115], v[144:147], v[204:207], v[112:115]
	v_mfma_f32_16x16x32_bf16 v[116:119], v[170:173], v[204:207], v[116:119]
	v_mfma_f32_16x16x32_bf16 v[104:107], v[144:147], v[212:215], v[104:107]
	v_mfma_f32_16x16x32_bf16 v[108:111], v[170:173], v[212:215], v[108:111]
	v_mfma_f32_16x16x32_bf16 v[96:99], v[144:147], v[220:223], v[96:99]
	v_mfma_f32_16x16x32_bf16 v[100:103], v[170:173], v[220:223], v[100:103]
	v_mfma_f32_16x16x32_bf16 v[120:123], v[166:169], v[200:203], v[120:123]
	v_mfma_f32_16x16x32_bf16 v[124:127], v[174:177], v[200:203], v[124:127]
	v_mfma_f32_16x16x32_bf16 v[112:115], v[166:169], v[208:211], v[112:115]
	v_mfma_f32_16x16x32_bf16 v[116:119], v[174:177], v[208:211], v[116:119]
	v_mfma_f32_16x16x32_bf16 v[104:107], v[166:169], v[216:219], v[104:107]
	v_mfma_f32_16x16x32_bf16 v[108:111], v[174:177], v[216:219], v[108:111]
	v_mfma_f32_16x16x32_bf16 v[96:99], v[166:169], v[224:227], v[96:99]
	v_mfma_f32_16x16x32_bf16 v[100:103], v[174:177], v[224:227], v[100:103]
	s_setprio 0
	s_setprio 1
	v_mfma_f32_16x16x32_bf16 v[76:79], v[178:181], v[196:199], v[76:79]
	v_mfma_f32_16x16x32_bf16 v[92:95], v[188:191], v[196:199], v[92:95]
	v_mfma_f32_16x16x32_bf16 v[72:75], v[178:181], v[204:207], v[72:75]
	v_mfma_f32_16x16x32_bf16 v[88:91], v[188:191], v[204:207], v[88:91]
	v_mfma_f32_16x16x32_bf16 v[68:71], v[178:181], v[212:215], v[68:71]
	v_mfma_f32_16x16x32_bf16 v[84:87], v[188:191], v[212:215], v[84:87]
	v_mfma_f32_16x16x32_bf16 v[64:67], v[178:181], v[220:223], v[64:67]
	v_mfma_f32_16x16x32_bf16 v[80:83], v[188:191], v[220:223], v[80:83]
	v_mfma_f32_16x16x32_bf16 v[76:79], v[184:187], v[200:203], v[76:79]
	v_mfma_f32_16x16x32_bf16 v[92:95], v[192:195], v[200:203], v[92:95]
	v_mfma_f32_16x16x32_bf16 v[72:75], v[184:187], v[208:211], v[72:75]
	v_mfma_f32_16x16x32_bf16 v[88:91], v[192:195], v[208:211], v[88:91]
	v_mfma_f32_16x16x32_bf16 v[68:71], v[184:187], v[216:219], v[68:71]
	v_mfma_f32_16x16x32_bf16 v[84:87], v[192:195], v[216:219], v[84:87]
	v_mfma_f32_16x16x32_bf16 v[64:67], v[184:187], v[224:227], v[64:67]
	v_mfma_f32_16x16x32_bf16 v[80:83], v[192:195], v[224:227], v[80:83]
	s_barrier
	s_setprio 0
	s_add_i32 s57, s46, s33
	v_lshl_add_u64 v[148:149], s[34:35], 0, v[128:129]
	s_mov_b32 m0, s57
	ds_read_b128 v[196:199], v163 offset:16384
	ds_read_b128 v[200:203], v163 offset:17408
	ds_read_b128 v[204:207], v163 offset:18432
	ds_read_b128 v[208:211], v163 offset:19456
	ds_read_b128 v[212:215], v163 offset:20480
	ds_read_b128 v[216:219], v163 offset:21504
	ds_read_b128 v[220:223], v163 offset:22528
	ds_read_b128 v[224:227], v163 offset:23552
	global_load_lds_dwordx4 v[148:149], off
	s_add_i32 m0, s57, 0x2000
	s_add_u32 s58, s34, 0x100000
	v_lshl_add_u64 v[228:229], s[34:35], 0, v[130:131]
	s_addc_u32 s59, s35, 0
	s_add_i32 s57, s47, s33
	global_load_lds_dwordx4 v[228:229], off
	v_lshl_add_u64 v[230:231], s[58:59], 0, v[128:129]
	s_mov_b32 m0, s57
	v_lshl_add_u64 v[232:233], s[36:37], 0, v[130:131]
	global_load_lds_dwordx4 v[230:231], off
	v_lshl_add_u64 v[230:231], s[58:59], 0, v[130:131]
	s_add_i32 m0, s57, 0x2000
	s_nop 0
	global_load_lds_dwordx4 v[230:231], off
	v_lshl_add_u64 v[230:231], s[36:37], 0, v[128:129]
	s_mov_b32 m0, s29
	s_nop 0
	global_load_lds_dwordx4 v[230:231], off
	s_mov_b32 m0, s38
	s_nop 0
	global_load_lds_dwordx4 v[232:233], off
	s_waitcnt vmcnt(8)
	s_waitcnt lgkmcnt(0)
	s_setprio 1
	s_barrier
; #define PG8_STAGE(bufoff, gbase, voff) do { _Pragma("unroll") for (int _i = 0; _i < 2; ++_i) \
;         __builtin_amdgcn_global_load_lds((const unsigned*)((const char*)(gbase) + (voff)[_i]), (PG8_LAS unsigned*)(lds + (bufoff) + ldsw + _i * 8192), 16, 0, 0); } while (0)
; #define PG8_LDA(dst, b, h) do { _Pragma("unroll") for (int m = 0; m < 4; ++m) _Pragma("unroll") for (int k = 0; k < 2; ++k) dst[m][k] = *(const PG8_LAS bf16x8*)(lds + PG8_SA(b, h) + aoff + m * 2048 + k * 1024); } while (0)
; #define PG8_LDB(dst, b, h) do { _Pragma("unroll") for (int n = 0; n < 2; ++n) _Pragma("unroll") for (int k = 0; k < 2; ++k) dst[n][k] = *(const PG8_LAS bf16x8*)(lds + PG8_SB(b, h) + boff + n * 2048 + k * 1024); } while (0)
; #define PG8_MMA(ai, bj, At, Bt) do { __builtin_amdgcn_s_setprio(1); _Pragma("unroll") for (int m = 0; m < 4; ++m) _Pragma("unroll") for (int n = 0; n < 2; ++n) _Pragma("unroll") for (int k = 0; k < 2; ++k) \
;         acc[ai][bj][m][n] = __builtin_amdgcn_mfma_f32_16x16x32_bf16(Bt[n][k], At[m][k], acc[ai][bj][m][n], 0, 0, 0); __builtin_amdgcn_s_setprio(0); } while (0)
; #define PG8_WAIT_V(n) asm volatile("s_waitcnt vmcnt(" #n ")" ::: "memory")
; #define PG8_WAIT_L(n) asm volatile("s_waitcnt lgkmcnt(" #n ")" ::: "memory")
; #define PG8_BAR __builtin_amdgcn_s_barrier()
; #define PG8_SCHED __builtin_amdgcn_sched_barrier(0)
; template <class Epi, class Sched, bool ALIGN_EPI = false, bool SP2 = false>
; __device__ __forceinline__ void gemm_phase(PG8_LAS unsigned char* lds, const Gemm g, const Sched& S, const Epi& E) {
;     ...
;             PG8_WAIT_V(8); PG8_WAIT_L(0); PG8_BAR; PG8_MMA(1, 0, At, B0); PG8_MMA(1, 1, At, B1); PG8_BAR; PG8_SCHED;
;             PG8_LDB(B0, 1, 0); PG8_LDB(B1, 1, 1); PG8_SCHED; PG8_LDA(At, 1, 0); PG8_STAGE(PG8_SA(0, 1), a2 + hstep, voffA);
;             PG8_WAIT_V(8); PG8_WAIT_L(0); PG8_BAR; PG8_MMA(0, 0, At, B0); PG8_MMA(0, 1, At, B1); PG8_BAR; PG8_SCHED;
	s_waitcnt lgkmcnt(0)
	v_mfma_f32_16x16x32_bf16 v[56:59], v[144:147], v[196:199], v[56:59]
	v_mfma_f32_16x16x32_bf16 v[60:63], v[170:173], v[196:199], v[60:63]
	v_mfma_f32_16x16x32_bf16 v[48:51], v[144:147], v[204:207], v[48:51]
	v_mfma_f32_16x16x32_bf16 v[52:55], v[170:173], v[204:207], v[52:55]
	v_mfma_f32_16x16x32_bf16 v[40:43], v[144:147], v[212:215], v[40:43]
	v_mfma_f32_16x16x32_bf16 v[44:47], v[170:173], v[212:215], v[44:47]
	v_mfma_f32_16x16x32_bf16 v[32:35], v[144:147], v[220:223], v[32:35]
	v_mfma_f32_16x16x32_bf16 v[36:39], v[170:173], v[220:223], v[36:39]
	v_mfma_f32_16x16x32_bf16 v[56:59], v[166:169], v[200:203], v[56:59]
	v_mfma_f32_16x16x32_bf16 v[60:63], v[174:177], v[200:203], v[60:63]
	v_mfma_f32_16x16x32_bf16 v[48:51], v[166:169], v[208:211], v[48:51]
	v_mfma_f32_16x16x32_bf16 v[52:55], v[174:177], v[208:211], v[52:55]
	v_mfma_f32_16x16x32_bf16 v[40:43], v[166:169], v[216:219], v[40:43]
	v_mfma_f32_16x16x32_bf16 v[44:47], v[174:177], v[216:219], v[44:47]
	v_mfma_f32_16x16x32_bf16 v[32:35], v[166:169], v[224:227], v[32:35]
	v_mfma_f32_16x16x32_bf16 v[36:39], v[174:177], v[224:227], v[36:39]
	s_setprio 0
	s_setprio 1
	v_mfma_f32_16x16x32_bf16 v[12:15], v[178:181], v[196:199], v[12:15]
	v_mfma_f32_16x16x32_bf16 v[28:31], v[188:191], v[196:199], v[28:31]
	v_mfma_f32_16x16x32_bf16 v[8:11], v[178:181], v[204:207], v[8:11]
	v_mfma_f32_16x16x32_bf16 v[24:27], v[188:191], v[204:207], v[24:27]
	v_mfma_f32_16x16x32_bf16 v[4:7], v[178:181], v[212:215], v[4:7]
	v_mfma_f32_16x16x32_bf16 v[20:23], v[188:191], v[212:215], v[20:23]
	v_mfma_f32_16x16x32_bf16 v[0:3], v[178:181], v[220:223], v[0:3]
	v_mfma_f32_16x16x32_bf16 v[16:19], v[188:191], v[220:223], v[16:19]
	v_mfma_f32_16x16x32_bf16 v[12:15], v[184:187], v[200:203], v[12:15]
	v_mfma_f32_16x16x32_bf16 v[28:31], v[192:195], v[200:203], v[28:31]
	v_mfma_f32_16x16x32_bf16 v[8:11], v[184:187], v[208:211], v[8:11]
	v_mfma_f32_16x16x32_bf16 v[24:27], v[192:195], v[208:211], v[24:27]
	v_mfma_f32_16x16x32_bf16 v[4:7], v[184:187], v[216:219], v[4:7]
	v_mfma_f32_16x16x32_bf16 v[20:23], v[192:195], v[216:219], v[20:23]
	v_mfma_f32_16x16x32_bf16 v[0:3], v[184:187], v[224:227], v[0:3]
	v_mfma_f32_16x16x32_bf16 v[16:19], v[192:195], v[224:227], v[16:19]
	s_barrier
	s_setprio 0
	s_add_i32 s57, 0, 0x18000
	v_add_u32_e32 v134, s57, v161
	s_add_i32 s58, 0, 0x1c000
	ds_read_b128 v[144:147], v134
	ds_read_b128 v[166:169], v134 offset:1024
	ds_read_b128 v[170:173], v134 offset:2048
	ds_read_b128 v[174:177], v134 offset:3072
	v_add_u32_e32 v134, s58, v161
	ds_read_b128 v[178:181], v134
	ds_read_b128 v[184:187], v134 offset:1024
	ds_read_b128 v[188:191], v134 offset:2048
	ds_read_b128 v[192:195], v134 offset:3072
	s_add_u32 s36, s36, 0x100000
	s_addc_u32 s37, s37, 0
	s_mov_b32 m0, s39
	v_lshl_add_u64 v[234:235], s[36:37], 0, v[128:129]
	ds_read_b128 v[196:199], v163 offset:32768
	ds_read_b128 v[200:203], v163 offset:33792
	ds_read_b128 v[204:207], v163 offset:34816
	ds_read_b128 v[208:211], v163 offset:35840
	ds_read_b128 v[212:215], v163 offset:36864
	ds_read_b128 v[216:219], v163 offset:37888
	ds_read_b128 v[220:223], v163 offset:38912
	ds_read_b128 v[224:227], v163 offset:39936
	global_load_lds_dwordx4 v[234:235], off
	v_lshl_add_u64 v[234:235], s[36:37], 0, v[130:131]
	s_mov_b32 m0, s40
	s_nop 0
	global_load_lds_dwordx4 v[234:235], off
	s_waitcnt vmcnt(8)
	s_waitcnt lgkmcnt(0)
	s_setprio 1
	s_barrier
	s_waitcnt lgkmcnt(0)
	v_mfma_f32_16x16x32_bf16 v[120:123], v[144:147], v[196:199], v[120:123]
	v_mfma_f32_16x16x32_bf16 v[124:127], v[170:173], v[196:199], v[124:127]
	v_mfma_f32_16x16x32_bf16 v[112:115], v[144:147], v[204:207], v[112:115]
	v_mfma_f32_16x16x32_bf16 v[116:119], v[170:173], v[204:207], v[116:119]
	v_mfma_f32_16x16x32_bf16 v[104:107], v[144:147], v[212:215], v[104:107]
	v_mfma_f32_16x16x32_bf16 v[108:111], v[170:173], v[212:215], v[108:111]
	v_mfma_f32_16x16x32_bf16 v[96:99], v[144:147], v[220:223], v[96:99]
	v_mfma_f32_16x16x32_bf16 v[100:103], v[170:173], v[220:223], v[100:103]
	v_mfma_f32_16x16x32_bf16 v[120:123], v[166:169], v[200:203], v[120:123]
	v_mfma_f32_16x16x32_bf16 v[124:127], v[174:177], v[200:203], v[124:127]
	v_mfma_f32_16x16x32_bf16 v[112:115], v[166:169], v[208:211], v[112:115]
	v_mfma_f32_16x16x32_bf16 v[116:119], v[174:177], v[208:211], v[116:119]
	v_mfma_f32_16x16x32_bf16 v[104:107], v[166:169], v[216:219], v[104:107]
	v_mfma_f32_16x16x32_bf16 v[108:111], v[174:177], v[216:219], v[108:111]
	v_mfma_f32_16x16x32_bf16 v[96:99], v[166:169], v[224:227], v[96:99]
	v_mfma_f32_16x16x32_bf16 v[100:103], v[174:177], v[224:227], v[100:103]
	s_setprio 0
	s_setprio 1
	v_mfma_f32_16x16x32_bf16 v[76:79], v[178:181], v[196:199], v[76:79]
	v_mfma_f32_16x16x32_bf16 v[92:95], v[188:191], v[196:199], v[92:95]
	v_mfma_f32_16x16x32_bf16 v[72:75], v[178:181], v[204:207], v[72:75]
	v_mfma_f32_16x16x32_bf16 v[88:91], v[188:191], v[204:207], v[88:91]
	v_mfma_f32_16x16x32_bf16 v[68:71], v[178:181], v[212:215], v[68:71]
	v_mfma_f32_16x16x32_bf16 v[84:87], v[188:191], v[212:215], v[84:87]
	v_mfma_f32_16x16x32_bf16 v[64:67], v[178:181], v[220:223], v[64:67]
	v_mfma_f32_16x16x32_bf16 v[80:83], v[188:191], v[220:223], v[80:83]
	v_mfma_f32_16x16x32_bf16 v[76:79], v[184:187], v[200:203], v[76:79]
	v_mfma_f32_16x16x32_bf16 v[92:95], v[192:195], v[200:203], v[92:95]
	v_mfma_f32_16x16x32_bf16 v[72:75], v[184:187], v[208:211], v[72:75]
	v_mfma_f32_16x16x32_bf16 v[88:91], v[192:195], v[208:211], v[88:91]
	v_mfma_f32_16x16x32_bf16 v[68:71], v[184:187], v[216:219], v[68:71]
	v_mfma_f32_16x16x32_bf16 v[84:87], v[192:195], v[216:219], v[84:87]
	v_mfma_f32_16x16x32_bf16 v[64:67], v[184:187], v[224:227], v[64:67]
	v_mfma_f32_16x16x32_bf16 v[80:83], v[192:195], v[224:227], v[80:83]
	s_barrier
; #define PG8_STAGE(bufoff, gbase, voff) do { _Pragma("unroll") for (int _i = 0; _i < 2; ++_i) \
;         __builtin_amdgcn_global_load_lds((const unsigned*)((const char*)(gbase) + (voff)[_i]), (PG8_LAS unsigned*)(lds + (bufoff) + ldsw + _i * 8192), 16, 0, 0); } while (0)
; #define PG8_LDA(dst, b, h) do { _Pragma("unroll") for (int m = 0; m < 4; ++m) _Pragma("unroll") for (int k = 0; k < 2; ++k) dst[m][k] = *(const PG8_LAS bf16x8*)(lds + PG8_SA(b, h) + aoff + m * 2048 + k * 1024); } while (0)
; #define PG8_MMA(ai, bj, At, Bt) do { __builtin_amdgcn_s_setprio(1); _Pragma("unroll") for (int m = 0; m < 4; ++m) _Pragma("unroll") for (int n = 0; n < 2; ++n) _Pragma("unroll") for (int k = 0; k < 2; ++k) \
;         acc[ai][bj][m][n] = __builtin_amdgcn_mfma_f32_16x16x32_bf16(Bt[n][k], At[m][k], acc[ai][bj][m][n], 0, 0, 0); __builtin_amdgcn_s_setprio(0); } while (0)
; #define PG8_WAIT_V(n) asm volatile("s_waitcnt vmcnt(" #n ")" ::: "memory")
; #define PG8_WAIT_L(n) asm volatile("s_waitcnt lgkmcnt(" #n ")" ::: "memory")
; #define PG8_BAR __builtin_amdgcn_s_barrier()
; #define PG8_SCHED __builtin_amdgcn_sched_barrier(0)
; template <class Epi, class Sched, bool ALIGN_EPI = false, bool SP2 = false>
; __device__ __forceinline__ void gemm_phase(PG8_LAS unsigned char* lds, const Gemm g, const Sched& S, const Epi& E) {
;     ...
;             PG8_LDA(At, 1, 1); PG8_STAGE(PG8_SB(1, 0), b3, voffB); PG8_STAGE(PG8_SB(1, 1), b3 + hstep, voffB); PG8_STAGE(PG8_SA(1, 0), a3, voffA);
;             PG8_WAIT_V(8); PG8_WAIT_L(0); PG8_BAR; PG8_MMA(1, 0, At, B0); PG8_MMA(1, 1, At, B1); PG8_BAR; PG8_SCHED;
	s_setprio 0
	s_add_i32 s36, s57, s33
	v_lshl_add_u64 v[148:149], v[148:149], 0, s[14:15]
	s_mov_b32 m0, s36
	ds_read_b128 v[196:199], v163 offset:49152
	ds_read_b128 v[200:203], v163 offset:50176
	ds_read_b128 v[204:207], v163 offset:51200
	ds_read_b128 v[208:211], v163 offset:52224
	ds_read_b128 v[212:215], v163 offset:53248
	ds_read_b128 v[216:219], v163 offset:54272
	ds_read_b128 v[220:223], v163 offset:55296
	ds_read_b128 v[224:227], v163 offset:56320
	global_load_lds_dwordx4 v[148:149], off
	s_add_i32 m0, s36, 0x2000
	s_add_u32 s34, s34, 0x100080
	v_lshl_add_u64 v[148:149], v[228:229], 0, s[14:15]
	s_addc_u32 s35, s35, 0
	s_add_i32 s36, s58, s33
	global_load_lds_dwordx4 v[148:149], off
	v_lshl_add_u64 v[148:149], s[34:35], 0, v[128:129]
	s_mov_b32 m0, s36
	s_nop 0
	global_load_lds_dwordx4 v[148:149], off
	v_lshl_add_u64 v[148:149], s[34:35], 0, v[130:131]
	s_add_i32 m0, s36, 0x2000
	s_nop 0
	global_load_lds_dwordx4 v[148:149], off
	v_lshl_add_u64 v[148:149], v[230:231], 0, s[14:15]
	s_mov_b32 m0, s41
	s_nop 0
	global_load_lds_dwordx4 v[148:149], off
	v_lshl_add_u64 v[148:149], v[232:233], 0, s[14:15]
	s_mov_b32 m0, s42
	s_nop 0
	global_load_lds_dwordx4 v[148:149], off
	s_waitcnt vmcnt(8)
	s_waitcnt lgkmcnt(0)
	s_setprio 1
	s_barrier
	s_waitcnt lgkmcnt(0)
	v_mfma_f32_16x16x32_bf16 v[56:59], v[144:147], v[196:199], v[56:59]
	v_mfma_f32_16x16x32_bf16 v[60:63], v[170:173], v[196:199], v[60:63]
	v_mfma_f32_16x16x32_bf16 v[48:51], v[144:147], v[204:207], v[48:51]
	v_mfma_f32_16x16x32_bf16 v[52:55], v[170:173], v[204:207], v[52:55]
	v_mfma_f32_16x16x32_bf16 v[40:43], v[144:147], v[212:215], v[40:43]
	v_mfma_f32_16x16x32_bf16 v[44:47], v[170:173], v[212:215], v[44:47]
	v_mfma_f32_16x16x32_bf16 v[32:35], v[144:147], v[220:223], v[32:35]
	v_mfma_f32_16x16x32_bf16 v[36:39], v[170:173], v[220:223], v[36:39]
	v_mfma_f32_16x16x32_bf16 v[56:59], v[166:169], v[200:203], v[56:59]
	v_mfma_f32_16x16x32_bf16 v[60:63], v[174:177], v[200:203], v[60:63]
	v_mfma_f32_16x16x32_bf16 v[48:51], v[166:169], v[208:211], v[48:51]
	v_mfma_f32_16x16x32_bf16 v[52:55], v[174:177], v[208:211], v[52:55]
	v_mfma_f32_16x16x32_bf16 v[40:43], v[166:169], v[216:219], v[40:43]
	v_mfma_f32_16x16x32_bf16 v[44:47], v[174:177], v[216:219], v[44:47]
	v_mfma_f32_16x16x32_bf16 v[32:35], v[166:169], v[224:227], v[32:35]
	v_mfma_f32_16x16x32_bf16 v[36:39], v[174:177], v[224:227], v[36:39]
	s_setprio 0
	s_setprio 1
	v_mfma_f32_16x16x32_bf16 v[12:15], v[178:181], v[196:199], v[12:15]
	v_mfma_f32_16x16x32_bf16 v[28:31], v[188:191], v[196:199], v[28:31]
	v_mfma_f32_16x16x32_bf16 v[8:11], v[178:181], v[204:207], v[8:11]
	v_mfma_f32_16x16x32_bf16 v[24:27], v[188:191], v[204:207], v[24:27]
	v_mfma_f32_16x16x32_bf16 v[4:7], v[178:181], v[212:215], v[4:7]
	v_mfma_f32_16x16x32_bf16 v[20:23], v[188:191], v[212:215], v[20:23]
	v_mfma_f32_16x16x32_bf16 v[0:3], v[178:181], v[220:223], v[0:3]
	v_mfma_f32_16x16x32_bf16 v[16:19], v[188:191], v[220:223], v[16:19]
	v_mfma_f32_16x16x32_bf16 v[12:15], v[184:187], v[200:203], v[12:15]
	v_mfma_f32_16x16x32_bf16 v[28:31], v[192:195], v[200:203], v[28:31]
	v_mfma_f32_16x16x32_bf16 v[8:11], v[184:187], v[208:211], v[8:11]
	v_mfma_f32_16x16x32_bf16 v[24:27], v[192:195], v[208:211], v[24:27]
	v_mfma_f32_16x16x32_bf16 v[4:7], v[184:187], v[216:219], v[4:7]
	v_mfma_f32_16x16x32_bf16 v[20:23], v[192:195], v[216:219], v[20:23]
	v_mfma_f32_16x16x32_bf16 v[0:3], v[184:187], v[224:227], v[0:3]
	v_mfma_f32_16x16x32_bf16 v[16:19], v[192:195], v[224:227], v[16:19]
	s_barrier
	s_setprio 0
	s_add_i32 s56, s56, 2
	s_add_u32 s30, s30, 0x100
	s_addc_u32 s31, s31, 0
	s_add_u32 s54, s54, 0x100
	s_addc_u32 s55, s55, 0
	s_cmp_gt_u32 s56, 61
	s_cbranch_scc0 .LBB0_1343
	s_and_b64 vcc, exec, s[16:17]
	s_cbranch_vccz .LBB0_1346
	s_barrier
